# K-loop SP1 load segments: all 16 fragment ds_reads issued before the LDS-DMA loads
# speedup vs baseline: 1.0017x; 1.0017x over previous
; #define PG8_STAGE(bufoff, gbase, voff) do { _Pragma("unroll") for (int _i = 0; _i < 2; ++_i) \
;         __builtin_amdgcn_global_load_lds((const unsigned*)((const char*)(gbase) + (voff)[_i]), (PG8_LAS unsigned*)(lds + (bufoff) + ldsw + _i * 8192), 16, 0, 0); } while (0)
; #define PG8_LDA(dst, b, h) do { _Pragma("unroll") for (int m = 0; m < 4; ++m) _Pragma("unroll") for (int k = 0; k < 2; ++k) dst[m][k] = *(const PG8_LAS bf16x8*)(lds + PG8_SA(b, h) + aoff + m * 2048 + k * 1024); } while (0)
; #define PG8_LDB(dst, b, h) do { _Pragma("unroll") for (int n = 0; n < 2; ++n) _Pragma("unroll") for (int k = 0; k < 2; ++k) dst[n][k] = *(const PG8_LAS bf16x8*)(lds + PG8_SB(b, h) + boff + n * 2048 + k * 1024); } while (0)
; #define PG8_MMA(ai, bj, At, Bt) do { __builtin_amdgcn_s_setprio(1); _Pragma("unroll") for (int m = 0; m < 4; ++m) _Pragma("unroll") for (int n = 0; n < 2; ++n) _Pragma("unroll") for (int k = 0; k < 2; ++k) \
;         acc[ai][bj][m][n] = __builtin_amdgcn_mfma_f32_16x16x32_bf16(Bt[n][k], At[m][k], acc[ai][bj][m][n], 0, 0, 0); __builtin_amdgcn_s_setprio(0); } while (0)
; #define PG8_WAIT_V(n) asm volatile("s_waitcnt vmcnt(" #n ")" ::: "memory")
; #define PG8_WAIT_L(n) asm volatile("s_waitcnt lgkmcnt(" #n ")" ::: "memory")
; #define PG8_BAR __builtin_amdgcn_s_barrier()
; #define PG8_SCHED __builtin_amdgcn_sched_barrier(0)
; template <class Epi, class Sched, bool ALIGN_EPI = false, bool SP2 = false, bool KSEG = false>
; __device__ __forceinline__ void gemm_phase(PG8_LAS unsigned char* lds, const Gemm g, const Sched& S, const Epi& E) {
;     ...
;             PG8_LDB(B0, 0, 0); PG8_LDB(B1, 0, 1); PG8_SCHED; PG8_LDA(At, 0, 0); PG8_STAGE(PG8_SA(1, 1), a1 + hstep, voffA);
;             PG8_WAIT_V(8); PG8_WAIT_L(0); PG8_BAR; PG8_MMA(0, 0, At, B0); PG8_MMA(0, 1, At, B1); PG8_BAR; PG8_SCHED;
;             PG8_LDA(At, 0, 1); PG8_STAGE(PG8_SB(0, 0), b2, voffB); PG8_STAGE(PG8_SB(0, 1), b2 + hstep, voffB); PG8_STAGE(PG8_SA(0, 0), a2, voffA);
;             PG8_WAIT_V(8); PG8_WAIT_L(0); PG8_BAR; PG8_MMA(1, 0, At, B0); PG8_MMA(1, 1, At, B1); PG8_BAR; PG8_SCHED;
.LBB0_120:
	ds_read_b128 v[146:149], v156
	ds_read_b128 v[150:153], v156 offset:1024
	ds_read_b128 v[160:163], v156 offset:2048
	ds_read_b128 v[164:167], v156 offset:3072
	ds_read_b128 v[168:171], v157
	ds_read_b128 v[172:175], v157 offset:1024
	ds_read_b128 v[176:179], v157 offset:2048
	ds_read_b128 v[180:183], v157 offset:3072
	ds_read_b128 v[184:187], v158
	ds_read_b128 v[188:191], v158 offset:1024
	ds_read_b128 v[192:195], v158 offset:2048
	ds_read_b128 v[196:199], v158 offset:3072
	ds_read_b128 v[200:203], v158 offset:4096
	ds_read_b128 v[204:207], v158 offset:5120
	ds_read_b128 v[208:211], v158 offset:6144
	ds_read_b128 v[212:215], v158 offset:7168
	s_mov_b32 m0, s51
	v_lshl_add_u64 v[216:217], s[98:99], 0, v[136:137]
	global_load_lds_dwordx4 v[216:217], off
	s_mov_b32 m0, s58
	v_lshl_add_u64 v[216:217], s[98:99], 0, v[132:133]
	global_load_lds_dwordx4 v[216:217], off
	v_lshl_add_u64 v[216:217], s[28:29], 0, v[138:139]
	s_add_i32 m0, s27, 0xc000
	s_nop 0
	global_load_lds_dwordx4 v[216:217], off
	s_add_i32 m0, s27, 0xe000
	v_lshl_add_u64 v[216:217], s[28:29], 0, v[140:141]
	global_load_lds_dwordx4 v[216:217], off
	s_waitcnt vmcnt(8) lgkmcnt(0)
	s_barrier
	s_setprio 1
	v_mfma_f32_16x16x32_bf16 v[126:129], v[146:149], v[184:187], v[126:129]
	v_mfma_f32_16x16x32_bf16 v[122:125], v[160:163], v[184:187], v[122:125]
	v_mfma_f32_16x16x32_bf16 v[110:113], v[146:149], v[192:195], v[110:113]
	v_mfma_f32_16x16x32_bf16 v[106:109], v[160:163], v[192:195], v[106:109]
	v_mfma_f32_16x16x32_bf16 v[94:97], v[146:149], v[200:203], v[94:97]
	v_mfma_f32_16x16x32_bf16 v[90:93], v[160:163], v[200:203], v[90:93]
	v_mfma_f32_16x16x32_bf16 v[78:81], v[146:149], v[208:211], v[78:81]
	v_mfma_f32_16x16x32_bf16 v[74:77], v[160:163], v[208:211], v[74:77]
	v_mfma_f32_16x16x32_bf16 v[126:129], v[150:153], v[188:191], v[126:129]
	v_mfma_f32_16x16x32_bf16 v[122:125], v[164:167], v[188:191], v[122:125]
	v_mfma_f32_16x16x32_bf16 v[110:113], v[150:153], v[196:199], v[110:113]
	v_mfma_f32_16x16x32_bf16 v[106:109], v[164:167], v[196:199], v[106:109]
	v_mfma_f32_16x16x32_bf16 v[94:97], v[150:153], v[204:207], v[94:97]
	v_mfma_f32_16x16x32_bf16 v[90:93], v[164:167], v[204:207], v[90:93]
	v_mfma_f32_16x16x32_bf16 v[78:81], v[150:153], v[212:215], v[78:81]
	v_mfma_f32_16x16x32_bf16 v[74:77], v[164:167], v[212:215], v[74:77]
	s_setprio 0
	s_setprio 1
	v_mfma_f32_16x16x32_bf16 v[118:121], v[168:171], v[184:187], v[118:121]
	v_mfma_f32_16x16x32_bf16 v[114:117], v[176:179], v[184:187], v[114:117]
	v_mfma_f32_16x16x32_bf16 v[102:105], v[168:171], v[192:195], v[102:105]
	v_mfma_f32_16x16x32_bf16 v[98:101], v[176:179], v[192:195], v[98:101]
	v_mfma_f32_16x16x32_bf16 v[86:89], v[168:171], v[200:203], v[86:89]
	v_mfma_f32_16x16x32_bf16 v[82:85], v[176:179], v[200:203], v[82:85]
	v_mfma_f32_16x16x32_bf16 v[70:73], v[168:171], v[208:211], v[70:73]
	v_mfma_f32_16x16x32_bf16 v[66:69], v[176:179], v[208:211], v[66:69]
	v_mfma_f32_16x16x32_bf16 v[118:121], v[172:175], v[188:191], v[118:121]
	v_mfma_f32_16x16x32_bf16 v[114:117], v[180:183], v[188:191], v[114:117]
	v_mfma_f32_16x16x32_bf16 v[102:105], v[172:175], v[196:199], v[102:105]
	v_mfma_f32_16x16x32_bf16 v[98:101], v[180:183], v[196:199], v[98:101]
	v_mfma_f32_16x16x32_bf16 v[86:89], v[172:175], v[204:207], v[86:89]
	v_mfma_f32_16x16x32_bf16 v[82:85], v[180:183], v[204:207], v[82:85]
	v_mfma_f32_16x16x32_bf16 v[70:73], v[172:175], v[212:215], v[70:73]
	v_mfma_f32_16x16x32_bf16 v[66:69], v[180:183], v[212:215], v[66:69]
	s_setprio 0
	s_barrier
	s_add_i32 s33, s60, s44
	v_lshl_add_u64 v[216:217], s[30:31], 0, v[134:135]
	s_mov_b32 m0, s33
	ds_read_b128 v[184:187], v158 offset:16384
	ds_read_b128 v[188:191], v158 offset:17408
	ds_read_b128 v[192:195], v158 offset:18432
	ds_read_b128 v[196:199], v158 offset:19456
	ds_read_b128 v[200:203], v158 offset:20480
	ds_read_b128 v[204:207], v158 offset:21504
	ds_read_b128 v[208:211], v158 offset:22528
	ds_read_b128 v[212:215], v158 offset:23552
	global_load_lds_dwordx4 v[216:217], off
	s_add_i32 m0, s33, 0x2000
	s_add_u32 s84, s30, 0x80000
	v_lshl_add_u64 v[218:219], s[30:31], 0, v[130:131]
	s_addc_u32 s85, s31, 0
	s_add_i32 s33, s61, s44
	global_load_lds_dwordx4 v[218:219], off
	s_mov_b32 m0, s33
	v_lshl_add_u64 v[220:221], s[84:85], 0, v[134:135]
	global_load_lds_dwordx4 v[220:221], off
	s_add_i32 m0, s33, 0x2000
	v_lshl_add_u64 v[220:221], s[84:85], 0, v[130:131]
	global_load_lds_dwordx4 v[220:221], off
	s_waitcnt vmcnt(6) lgkmcnt(0)
	s_barrier
	s_setprio 1
	v_mfma_f32_16x16x32_bf16 v[62:65], v[146:149], v[184:187], v[62:65]
	v_mfma_f32_16x16x32_bf16 v[58:61], v[160:163], v[184:187], v[58:61]
	v_mfma_f32_16x16x32_bf16 v[46:49], v[146:149], v[192:195], v[46:49]
	v_mfma_f32_16x16x32_bf16 v[42:45], v[160:163], v[192:195], v[42:45]
	v_mfma_f32_16x16x32_bf16 v[30:33], v[146:149], v[200:203], v[30:33]
	v_mfma_f32_16x16x32_bf16 v[26:29], v[160:163], v[200:203], v[26:29]
	v_mfma_f32_16x16x32_bf16 v[14:17], v[146:149], v[208:211], v[14:17]
	v_mfma_f32_16x16x32_bf16 v[10:13], v[160:163], v[208:211], v[10:13]
	v_mfma_f32_16x16x32_bf16 v[62:65], v[150:153], v[188:191], v[62:65]
	v_mfma_f32_16x16x32_bf16 v[58:61], v[164:167], v[188:191], v[58:61]
	v_mfma_f32_16x16x32_bf16 v[46:49], v[150:153], v[196:199], v[46:49]
	v_mfma_f32_16x16x32_bf16 v[42:45], v[164:167], v[196:199], v[42:45]
	v_mfma_f32_16x16x32_bf16 v[30:33], v[150:153], v[204:207], v[30:33]
	v_mfma_f32_16x16x32_bf16 v[26:29], v[164:167], v[204:207], v[26:29]
	v_mfma_f32_16x16x32_bf16 v[14:17], v[150:153], v[212:215], v[14:17]
	v_mfma_f32_16x16x32_bf16 v[10:13], v[164:167], v[212:215], v[10:13]
	s_setprio 0
	s_setprio 1
	v_mfma_f32_16x16x32_bf16 v[54:57], v[168:171], v[184:187], v[54:57]
	v_mfma_f32_16x16x32_bf16 v[50:53], v[176:179], v[184:187], v[50:53]
	v_mfma_f32_16x16x32_bf16 v[38:41], v[168:171], v[192:195], v[38:41]
	v_mfma_f32_16x16x32_bf16 v[34:37], v[176:179], v[192:195], v[34:37]
	v_mfma_f32_16x16x32_bf16 v[22:25], v[168:171], v[200:203], v[22:25]
	v_mfma_f32_16x16x32_bf16 v[18:21], v[176:179], v[200:203], v[18:21]
	v_mfma_f32_16x16x32_bf16 v[6:9], v[168:171], v[208:211], v[6:9]
	v_mfma_f32_16x16x32_bf16 v[2:5], v[176:179], v[208:211], v[2:5]
	v_mfma_f32_16x16x32_bf16 v[54:57], v[172:175], v[188:191], v[54:57]
	v_mfma_f32_16x16x32_bf16 v[50:53], v[180:183], v[188:191], v[50:53]
	v_mfma_f32_16x16x32_bf16 v[38:41], v[172:175], v[196:199], v[38:41]
	v_mfma_f32_16x16x32_bf16 v[34:37], v[180:183], v[196:199], v[34:37]
	v_mfma_f32_16x16x32_bf16 v[22:25], v[172:175], v[204:207], v[22:25]
	v_mfma_f32_16x16x32_bf16 v[18:21], v[180:183], v[204:207], v[18:21]
	v_mfma_f32_16x16x32_bf16 v[6:9], v[172:175], v[212:215], v[6:9]
	v_mfma_f32_16x16x32_bf16 v[2:5], v[180:183], v[212:215], v[2:5]
	s_setprio 0
	s_barrier
; #define PG8_STAGE(bufoff, gbase, voff) do { _Pragma("unroll") for (int _i = 0; _i < 2; ++_i) \
;         __builtin_amdgcn_global_load_lds((const unsigned*)((const char*)(gbase) + (voff)[_i]), (PG8_LAS unsigned*)(lds + (bufoff) + ldsw + _i * 8192), 16, 0, 0); } while (0)
; #define PG8_LDA(dst, b, h) do { _Pragma("unroll") for (int m = 0; m < 4; ++m) _Pragma("unroll") for (int k = 0; k < 2; ++k) dst[m][k] = *(const PG8_LAS bf16x8*)(lds + PG8_SA(b, h) + aoff + m * 2048 + k * 1024); } while (0)
; #define PG8_LDB(dst, b, h) do { _Pragma("unroll") for (int n = 0; n < 2; ++n) _Pragma("unroll") for (int k = 0; k < 2; ++k) dst[n][k] = *(const PG8_LAS bf16x8*)(lds + PG8_SB(b, h) + boff + n * 2048 + k * 1024); } while (0)
; #define PG8_MMA(ai, bj, At, Bt) do { __builtin_amdgcn_s_setprio(1); _Pragma("unroll") for (int m = 0; m < 4; ++m) _Pragma("unroll") for (int n = 0; n < 2; ++n) _Pragma("unroll") for (int k = 0; k < 2; ++k) \
;         acc[ai][bj][m][n] = __builtin_amdgcn_mfma_f32_16x16x32_bf16(Bt[n][k], At[m][k], acc[ai][bj][m][n], 0, 0, 0); __builtin_amdgcn_s_setprio(0); } while (0)
; #define PG8_WAIT_V(n) asm volatile("s_waitcnt vmcnt(" #n ")" ::: "memory")
; #define PG8_WAIT_L(n) asm volatile("s_waitcnt lgkmcnt(" #n ")" ::: "memory")
; #define PG8_BAR __builtin_amdgcn_s_barrier()
; #define PG8_SCHED __builtin_amdgcn_sched_barrier(0)
; template <class Epi, class Sched, bool ALIGN_EPI = false, bool SP2 = false, bool KSEG = false>
; __device__ __forceinline__ void gemm_phase(PG8_LAS unsigned char* lds, const Gemm g, const Sched& S, const Epi& E) {
;     ...
;             PG8_LDB(B0, 1, 0); PG8_LDB(B1, 1, 1); PG8_SCHED; PG8_LDA(At, 1, 0); PG8_STAGE(PG8_SA(0, 1), a2 + hstep, voffA);
;             PG8_WAIT_V(8); PG8_WAIT_L(0); PG8_BAR; PG8_MMA(0, 0, At, B0); PG8_MMA(0, 1, At, B1); PG8_BAR; PG8_SCHED;
	s_add_i32 s33, 0, 0x18000
	v_add_u32_e32 v159, s33, v154
	s_add_i32 s81, 0, 0x1c000
	ds_read_b128 v[146:149], v159
	ds_read_b128 v[150:153], v159 offset:1024
	ds_read_b128 v[160:163], v159 offset:2048
	ds_read_b128 v[164:167], v159 offset:3072
	v_add_u32_e32 v159, s81, v154
	ds_read_b128 v[168:171], v159
	ds_read_b128 v[172:175], v159 offset:1024
	ds_read_b128 v[176:179], v159 offset:2048
	ds_read_b128 v[180:183], v159 offset:3072
	ds_read_b128 v[184:187], v158 offset:32768
	ds_read_b128 v[188:191], v158 offset:33792
	ds_read_b128 v[192:195], v158 offset:34816
	ds_read_b128 v[196:199], v158 offset:35840
	ds_read_b128 v[200:203], v158 offset:36864
	ds_read_b128 v[204:207], v158 offset:37888
	ds_read_b128 v[208:211], v158 offset:38912
	ds_read_b128 v[212:215], v158 offset:39936
	s_mov_b32 m0, s27
	v_lshl_add_u64 v[224:225], s[42:43], 0, v[136:137]
	global_load_lds_dwordx4 v[224:225], off
	s_mov_b32 m0, s47
	v_lshl_add_u64 v[224:225], s[42:43], 0, v[132:133]
	global_load_lds_dwordx4 v[224:225], off
	s_add_u32 s42, s42, 0x80000
	s_addc_u32 s43, s43, 0
	s_mov_b32 m0, s48
	v_lshl_add_u64 v[224:225], s[42:43], 0, v[136:137]
	global_load_lds_dwordx4 v[224:225], off
	s_mov_b32 m0, s49
	v_lshl_add_u64 v[224:225], s[42:43], 0, v[132:133]
	global_load_lds_dwordx4 v[224:225], off
	s_waitcnt vmcnt(8) lgkmcnt(0)
	s_barrier
	s_setprio 1
	v_mfma_f32_16x16x32_bf16 v[126:129], v[146:149], v[184:187], v[126:129]
	v_mfma_f32_16x16x32_bf16 v[122:125], v[160:163], v[184:187], v[122:125]
	v_mfma_f32_16x16x32_bf16 v[110:113], v[146:149], v[192:195], v[110:113]
	v_mfma_f32_16x16x32_bf16 v[106:109], v[160:163], v[192:195], v[106:109]
	v_mfma_f32_16x16x32_bf16 v[94:97], v[146:149], v[200:203], v[94:97]
	v_mfma_f32_16x16x32_bf16 v[90:93], v[160:163], v[200:203], v[90:93]
	v_mfma_f32_16x16x32_bf16 v[78:81], v[146:149], v[208:211], v[78:81]
	v_mfma_f32_16x16x32_bf16 v[74:77], v[160:163], v[208:211], v[74:77]
	v_mfma_f32_16x16x32_bf16 v[126:129], v[150:153], v[188:191], v[126:129]
	v_mfma_f32_16x16x32_bf16 v[122:125], v[164:167], v[188:191], v[122:125]
	v_mfma_f32_16x16x32_bf16 v[110:113], v[150:153], v[196:199], v[110:113]
	v_mfma_f32_16x16x32_bf16 v[106:109], v[164:167], v[196:199], v[106:109]
	v_mfma_f32_16x16x32_bf16 v[94:97], v[150:153], v[204:207], v[94:97]
	v_mfma_f32_16x16x32_bf16 v[90:93], v[164:167], v[204:207], v[90:93]
	v_mfma_f32_16x16x32_bf16 v[78:81], v[150:153], v[212:215], v[78:81]
	v_mfma_f32_16x16x32_bf16 v[74:77], v[164:167], v[212:215], v[74:77]
	s_setprio 0
	s_setprio 1
	v_mfma_f32_16x16x32_bf16 v[118:121], v[168:171], v[184:187], v[118:121]
	v_mfma_f32_16x16x32_bf16 v[114:117], v[176:179], v[184:187], v[114:117]
	v_mfma_f32_16x16x32_bf16 v[102:105], v[168:171], v[192:195], v[102:105]
	v_mfma_f32_16x16x32_bf16 v[98:101], v[176:179], v[192:195], v[98:101]
	v_mfma_f32_16x16x32_bf16 v[86:89], v[168:171], v[200:203], v[86:89]
	v_mfma_f32_16x16x32_bf16 v[82:85], v[176:179], v[200:203], v[82:85]
	v_mfma_f32_16x16x32_bf16 v[70:73], v[168:171], v[208:211], v[70:73]
	v_mfma_f32_16x16x32_bf16 v[66:69], v[176:179], v[208:211], v[66:69]
	v_mfma_f32_16x16x32_bf16 v[118:121], v[172:175], v[188:191], v[118:121]
	v_mfma_f32_16x16x32_bf16 v[114:117], v[180:183], v[188:191], v[114:117]
	v_mfma_f32_16x16x32_bf16 v[102:105], v[172:175], v[196:199], v[102:105]
	v_mfma_f32_16x16x32_bf16 v[98:101], v[180:183], v[196:199], v[98:101]
	v_mfma_f32_16x16x32_bf16 v[86:89], v[172:175], v[204:207], v[86:89]
	v_mfma_f32_16x16x32_bf16 v[82:85], v[180:183], v[204:207], v[82:85]
	v_mfma_f32_16x16x32_bf16 v[70:73], v[172:175], v[212:215], v[70:73]
	v_mfma_f32_16x16x32_bf16 v[66:69], v[180:183], v[212:215], v[66:69]
	s_setprio 0
	s_barrier
; #define PG8_STAGE(bufoff, gbase, voff) do { _Pragma("unroll") for (int _i = 0; _i < 2; ++_i) \
;         __builtin_amdgcn_global_load_lds((const unsigned*)((const char*)(gbase) + (voff)[_i]), (PG8_LAS unsigned*)(lds + (bufoff) + ldsw + _i * 8192), 16, 0, 0); } while (0)
; #define PG8_LDA(dst, b, h) do { _Pragma("unroll") for (int m = 0; m < 4; ++m) _Pragma("unroll") for (int k = 0; k < 2; ++k) dst[m][k] = *(const PG8_LAS bf16x8*)(lds + PG8_SA(b, h) + aoff + m * 2048 + k * 1024); } while (0)
; #define PG8_MMA(ai, bj, At, Bt) do { __builtin_amdgcn_s_setprio(1); _Pragma("unroll") for (int m = 0; m < 4; ++m) _Pragma("unroll") for (int n = 0; n < 2; ++n) _Pragma("unroll") for (int k = 0; k < 2; ++k) \
;         acc[ai][bj][m][n] = __builtin_amdgcn_mfma_f32_16x16x32_bf16(Bt[n][k], At[m][k], acc[ai][bj][m][n], 0, 0, 0); __builtin_amdgcn_s_setprio(0); } while (0)
; #define PG8_WAIT_V(n) asm volatile("s_waitcnt vmcnt(" #n ")" ::: "memory")
; #define PG8_WAIT_L(n) asm volatile("s_waitcnt lgkmcnt(" #n ")" ::: "memory")
; #define PG8_BAR __builtin_amdgcn_s_barrier()
; #define PG8_SCHED __builtin_amdgcn_sched_barrier(0)
; template <class Epi, class Sched, bool ALIGN_EPI = false, bool SP2 = false, bool KSEG = false>
; __device__ __forceinline__ void gemm_phase(PG8_LAS unsigned char* lds, const Gemm g, const Sched& S, const Epi& E) {
;     ...
;         for (int t = 0; t < nt; t += 2) {
;             const bool last = (t == nt - 2);
;             const char* a1 = cA + (size_t)(t + 1) * kstep;
;             const char* a2 = last ? nA : cA + (size_t)(t + 2) * kstep; const char* b2 = last ? nB : cB + (size_t)(t + 2) * kstep;
;             const char* a3 = a2 + kstep; const char* b3 = b2 + kstep;
;     ...
;             PG8_LDA(At, 1, 1); PG8_STAGE(PG8_SB(1, 0), b3, voffB); PG8_STAGE(PG8_SB(1, 1), b3 + hstep, voffB); PG8_STAGE(PG8_SA(1, 0), a3, voffA);
;             PG8_WAIT_V(8); PG8_WAIT_L(0); PG8_BAR; PG8_MMA(1, 0, At, B0); PG8_MMA(1, 1, At, B1); PG8_BAR; PG8_SCHED;
	s_add_i32 s33, s33, s44
	v_lshl_add_u64 v[216:217], v[216:217], 0, s[12:13]
	s_mov_b32 m0, s33
	ds_read_b128 v[184:187], v158 offset:49152
	ds_read_b128 v[188:191], v158 offset:50176
	ds_read_b128 v[192:195], v158 offset:51200
	ds_read_b128 v[196:199], v158 offset:52224
	ds_read_b128 v[200:203], v158 offset:53248
	ds_read_b128 v[204:207], v158 offset:54272
	ds_read_b128 v[208:211], v158 offset:55296
	ds_read_b128 v[212:215], v158 offset:56320
	global_load_lds_dwordx4 v[216:217], off
	s_add_i32 m0, s33, 0x2000
	s_add_u32 s30, s30, 0x80080
	v_lshl_add_u64 v[216:217], v[218:219], 0, s[12:13]
	s_addc_u32 s31, s31, 0
	s_add_i32 s33, s81, s44
	global_load_lds_dwordx4 v[216:217], off
	s_mov_b32 m0, s33
	v_lshl_add_u64 v[216:217], s[30:31], 0, v[134:135]
	global_load_lds_dwordx4 v[216:217], off
	s_add_i32 m0, s33, 0x2000
	v_lshl_add_u64 v[216:217], s[30:31], 0, v[130:131]
	global_load_lds_dwordx4 v[216:217], off
	s_waitcnt vmcnt(6) lgkmcnt(0)
	s_barrier
	s_setprio 1
	v_mfma_f32_16x16x32_bf16 v[62:65], v[146:149], v[184:187], v[62:65]
	v_mfma_f32_16x16x32_bf16 v[58:61], v[160:163], v[184:187], v[58:61]
	v_mfma_f32_16x16x32_bf16 v[46:49], v[146:149], v[192:195], v[46:49]
	v_mfma_f32_16x16x32_bf16 v[42:45], v[160:163], v[192:195], v[42:45]
	v_mfma_f32_16x16x32_bf16 v[30:33], v[146:149], v[200:203], v[30:33]
	v_mfma_f32_16x16x32_bf16 v[26:29], v[160:163], v[200:203], v[26:29]
	v_mfma_f32_16x16x32_bf16 v[14:17], v[146:149], v[208:211], v[14:17]
	v_mfma_f32_16x16x32_bf16 v[10:13], v[160:163], v[208:211], v[10:13]
	v_mfma_f32_16x16x32_bf16 v[62:65], v[150:153], v[188:191], v[62:65]
	v_mfma_f32_16x16x32_bf16 v[58:61], v[164:167], v[188:191], v[58:61]
	v_mfma_f32_16x16x32_bf16 v[46:49], v[150:153], v[196:199], v[46:49]
	v_mfma_f32_16x16x32_bf16 v[42:45], v[164:167], v[196:199], v[42:45]
	v_mfma_f32_16x16x32_bf16 v[30:33], v[150:153], v[204:207], v[30:33]
	v_mfma_f32_16x16x32_bf16 v[26:29], v[164:167], v[204:207], v[26:29]
	v_mfma_f32_16x16x32_bf16 v[14:17], v[150:153], v[212:215], v[14:17]
	v_mfma_f32_16x16x32_bf16 v[10:13], v[164:167], v[212:215], v[10:13]
	s_setprio 0
	s_setprio 1
	v_mfma_f32_16x16x32_bf16 v[54:57], v[168:171], v[184:187], v[54:57]
	s_add_i32 s80, s80, 2
	v_mfma_f32_16x16x32_bf16 v[50:53], v[176:179], v[184:187], v[50:53]
	s_add_u32 s28, s28, 0x100
	v_mfma_f32_16x16x32_bf16 v[38:41], v[168:171], v[192:195], v[38:41]
	s_addc_u32 s29, s29, 0
	v_mfma_f32_16x16x32_bf16 v[34:37], v[176:179], v[192:195], v[34:37]
	s_add_u32 s66, s66, 0x100
	v_mfma_f32_16x16x32_bf16 v[22:25], v[168:171], v[200:203], v[22:25]
	s_addc_u32 s67, s67, 0
	v_mfma_f32_16x16x32_bf16 v[18:21], v[176:179], v[200:203], v[18:21]
	s_add_u32 s30, s28, 0xfff80080
	v_mfma_f32_16x16x32_bf16 v[6:9], v[168:171], v[208:211], v[6:9]
	s_addc_u32 s31, s29, -1
	v_mfma_f32_16x16x32_bf16 v[2:5], v[176:179], v[208:211], v[2:5]
	s_cmp_eq_u32 s80, 28
	v_mfma_f32_16x16x32_bf16 v[54:57], v[172:175], v[188:191], v[54:57]
	s_cselect_b32 s43, s21, s31
	v_mfma_f32_16x16x32_bf16 v[50:53], v[180:183], v[188:191], v[50:53]
	s_cselect_b32 s42, s64, s30
	v_mfma_f32_16x16x32_bf16 v[38:41], v[172:175], v[196:199], v[38:41]
	s_cselect_b32 s31, s19, s67
	v_mfma_f32_16x16x32_bf16 v[34:37], v[180:183], v[196:199], v[34:37]
	s_cselect_b32 s30, s65, s66
	v_mfma_f32_16x16x32_bf16 v[22:25], v[172:175], v[204:207], v[22:25]
	s_add_u32 s98, s28, 0xfff80000
	v_mfma_f32_16x16x32_bf16 v[18:21], v[180:183], v[204:207], v[18:21]
	s_addc_u32 s99, s29, -1
	v_mfma_f32_16x16x32_bf16 v[6:9], v[172:175], v[212:215], v[6:9]
	s_cmp_gt_u32 s80, 29
	v_mfma_f32_16x16x32_bf16 v[2:5], v[180:183], v[212:215], v[2:5]
	s_setprio 0
	s_barrier
	s_cbranch_scc0 .LBB0_120
	s_and_b64 vcc, exec, s[16:17]
	s_cbranch_vccz .LBB0_123
	s_barrier

; #define PG8_STAGE(bufoff, gbase, voff) do { _Pragma("unroll") for (int _i = 0; _i < 2; ++_i) \
;         __builtin_amdgcn_global_load_lds((const unsigned*)((const char*)(gbase) + (voff)[_i]), (PG8_LAS unsigned*)(lds + (bufoff) + ldsw + _i * 8192), 16, 0, 0); } while (0)
; #define PG8_LDA(dst, b, h) do { _Pragma("unroll") for (int m = 0; m < 4; ++m) _Pragma("unroll") for (int k = 0; k < 2; ++k) dst[m][k] = *(const PG8_LAS bf16x8*)(lds + PG8_SA(b, h) + aoff + m * 2048 + k * 1024); } while (0)
; #define PG8_LDB(dst, b, h) do { _Pragma("unroll") for (int n = 0; n < 2; ++n) _Pragma("unroll") for (int k = 0; k < 2; ++k) dst[n][k] = *(const PG8_LAS bf16x8*)(lds + PG8_SB(b, h) + boff + n * 2048 + k * 1024); } while (0)
; #define PG8_MMA(ai, bj, At, Bt) do { __builtin_amdgcn_s_setprio(1); _Pragma("unroll") for (int m = 0; m < 4; ++m) _Pragma("unroll") for (int n = 0; n < 2; ++n) _Pragma("unroll") for (int k = 0; k < 2; ++k) \
;         acc[ai][bj][m][n] = __builtin_amdgcn_mfma_f32_16x16x32_bf16(Bt[n][k], At[m][k], acc[ai][bj][m][n], 0, 0, 0); __builtin_amdgcn_s_setprio(0); } while (0)
; #define PG8_WAIT_V(n) asm volatile("s_waitcnt vmcnt(" #n ")" ::: "memory")
; #define PG8_WAIT_L(n) asm volatile("s_waitcnt lgkmcnt(" #n ")" ::: "memory")
; #define PG8_BAR __builtin_amdgcn_s_barrier()
; #define PG8_SCHED __builtin_amdgcn_sched_barrier(0)
; template <class Epi, class Sched, bool ALIGN_EPI = false, bool SP2 = false, bool KSEG = false>
; __device__ __forceinline__ void gemm_phase(PG8_LAS unsigned char* lds, const Gemm g, const Sched& S, const Epi& E) {
;     ...
;             PG8_LDB(B0, 0, 0); PG8_LDB(B1, 0, 1); PG8_SCHED; PG8_LDA(At, 0, 0); PG8_STAGE(PG8_SA(1, 1), a1 + hstep, voffA);
;             PG8_WAIT_V(8); PG8_WAIT_L(0); PG8_BAR; PG8_MMA(0, 0, At, B0); PG8_MMA(0, 1, At, B1); PG8_BAR; PG8_SCHED;
;             PG8_LDA(At, 0, 1); PG8_STAGE(PG8_SB(0, 0), b2, voffB); PG8_STAGE(PG8_SB(0, 1), b2 + hstep, voffB); PG8_STAGE(PG8_SA(0, 0), a2, voffA);
;             PG8_WAIT_V(8); PG8_WAIT_L(0); PG8_BAR; PG8_MMA(1, 0, At, B0); PG8_MMA(1, 1, At, B1); PG8_BAR; PG8_SCHED;
.LBB0_497:
	ds_read_b128 v[148:151], v168
	ds_read_b128 v[172:175], v168 offset:1024
	ds_read_b128 v[176:179], v168 offset:2048
	ds_read_b128 v[180:183], v168 offset:3072
	ds_read_b128 v[184:187], v169
	ds_read_b128 v[188:191], v169 offset:1024
	ds_read_b128 v[192:195], v169 offset:2048
	ds_read_b128 v[196:199], v169 offset:3072
	ds_read_b128 v[200:203], v170
	ds_read_b128 v[204:207], v170 offset:1024
	ds_read_b128 v[208:211], v170 offset:2048
	ds_read_b128 v[212:215], v170 offset:3072
	ds_read_b128 v[216:219], v170 offset:4096
	ds_read_b128 v[220:223], v170 offset:5120
	ds_read_b128 v[224:227], v170 offset:6144
	ds_read_b128 v[228:231], v170 offset:7168
	s_mov_b32 m0, s52
	v_lshl_add_u64 v[232:233], s[98:99], 0, v[132:133]
	global_load_lds_dwordx4 v[232:233], off
	s_mov_b32 m0, s53
	v_lshl_add_u64 v[232:233], s[98:99], 0, v[136:137]
	global_load_lds_dwordx4 v[232:233], off
	v_lshl_add_u64 v[232:233], s[36:37], 0, v[140:141]
	s_add_i32 m0, s31, 0xc000
	s_nop 0
	global_load_lds_dwordx4 v[232:233], off
	s_add_i32 m0, s31, 0xe000
	v_lshl_add_u64 v[232:233], s[36:37], 0, v[142:143]
	global_load_lds_dwordx4 v[232:233], off
	s_waitcnt vmcnt(8) lgkmcnt(0)
	s_barrier
	s_setprio 1
	v_mfma_f32_16x16x32_bf16 v[126:129], v[148:151], v[200:203], v[126:129]
	v_mfma_f32_16x16x32_bf16 v[122:125], v[176:179], v[200:203], v[122:125]
	v_mfma_f32_16x16x32_bf16 v[110:113], v[148:151], v[208:211], v[110:113]
	v_mfma_f32_16x16x32_bf16 v[106:109], v[176:179], v[208:211], v[106:109]
	v_mfma_f32_16x16x32_bf16 v[94:97], v[148:151], v[216:219], v[94:97]
	v_mfma_f32_16x16x32_bf16 v[90:93], v[176:179], v[216:219], v[90:93]
	v_mfma_f32_16x16x32_bf16 v[78:81], v[148:151], v[224:227], v[78:81]
	v_mfma_f32_16x16x32_bf16 v[74:77], v[176:179], v[224:227], v[74:77]
	v_mfma_f32_16x16x32_bf16 v[126:129], v[172:175], v[204:207], v[126:129]
	v_mfma_f32_16x16x32_bf16 v[122:125], v[180:183], v[204:207], v[122:125]
	v_mfma_f32_16x16x32_bf16 v[110:113], v[172:175], v[212:215], v[110:113]
	v_mfma_f32_16x16x32_bf16 v[106:109], v[180:183], v[212:215], v[106:109]
	v_mfma_f32_16x16x32_bf16 v[94:97], v[172:175], v[220:223], v[94:97]
	v_mfma_f32_16x16x32_bf16 v[90:93], v[180:183], v[220:223], v[90:93]
	v_mfma_f32_16x16x32_bf16 v[78:81], v[172:175], v[228:231], v[78:81]
	v_mfma_f32_16x16x32_bf16 v[74:77], v[180:183], v[228:231], v[74:77]
	s_setprio 0
	s_setprio 1
	v_mfma_f32_16x16x32_bf16 v[118:121], v[184:187], v[200:203], v[118:121]
	v_mfma_f32_16x16x32_bf16 v[114:117], v[192:195], v[200:203], v[114:117]
	v_mfma_f32_16x16x32_bf16 v[102:105], v[184:187], v[208:211], v[102:105]
	v_mfma_f32_16x16x32_bf16 v[98:101], v[192:195], v[208:211], v[98:101]
	v_mfma_f32_16x16x32_bf16 v[86:89], v[184:187], v[216:219], v[86:89]
	v_mfma_f32_16x16x32_bf16 v[82:85], v[192:195], v[216:219], v[82:85]
	v_mfma_f32_16x16x32_bf16 v[70:73], v[184:187], v[224:227], v[70:73]
	v_mfma_f32_16x16x32_bf16 v[66:69], v[192:195], v[224:227], v[66:69]
	v_mfma_f32_16x16x32_bf16 v[118:121], v[188:191], v[204:207], v[118:121]
	v_mfma_f32_16x16x32_bf16 v[114:117], v[196:199], v[204:207], v[114:117]
	v_mfma_f32_16x16x32_bf16 v[102:105], v[188:191], v[212:215], v[102:105]
	v_mfma_f32_16x16x32_bf16 v[98:101], v[196:199], v[212:215], v[98:101]
	v_mfma_f32_16x16x32_bf16 v[86:89], v[188:191], v[220:223], v[86:89]
	v_mfma_f32_16x16x32_bf16 v[82:85], v[196:199], v[220:223], v[82:85]
	v_mfma_f32_16x16x32_bf16 v[70:73], v[188:191], v[228:231], v[70:73]
	v_mfma_f32_16x16x32_bf16 v[66:69], v[196:199], v[228:231], v[66:69]
	s_setprio 0
	s_barrier
	s_add_i32 s33, s54, s43
	v_lshl_add_u64 v[232:233], s[38:39], 0, v[134:135]
	s_mov_b32 m0, s33
	ds_read_b128 v[200:203], v170 offset:16384
	ds_read_b128 v[204:207], v170 offset:17408
	ds_read_b128 v[208:211], v170 offset:18432
	ds_read_b128 v[212:215], v170 offset:19456
	ds_read_b128 v[216:219], v170 offset:20480
	ds_read_b128 v[220:223], v170 offset:21504
	ds_read_b128 v[224:227], v170 offset:22528
	ds_read_b128 v[228:231], v170 offset:23552
	global_load_lds_dwordx4 v[232:233], off
	s_add_i32 m0, s33, 0x2000
	s_add_u32 s64, s38, 0x80000
	v_lshl_add_u64 v[234:235], s[38:39], 0, v[138:139]
	s_addc_u32 s65, s39, 0
	s_add_i32 s33, s55, s43
	global_load_lds_dwordx4 v[234:235], off
	s_mov_b32 m0, s33
	v_lshl_add_u64 v[236:237], s[64:65], 0, v[134:135]
	global_load_lds_dwordx4 v[236:237], off
	s_add_i32 m0, s33, 0x2000
	v_lshl_add_u64 v[236:237], s[64:65], 0, v[138:139]
	global_load_lds_dwordx4 v[236:237], off
	s_waitcnt vmcnt(6) lgkmcnt(0)
	s_barrier
	s_setprio 1
	v_mfma_f32_16x16x32_bf16 v[62:65], v[148:151], v[200:203], v[62:65]
	v_mfma_f32_16x16x32_bf16 v[58:61], v[176:179], v[200:203], v[58:61]
	v_mfma_f32_16x16x32_bf16 v[46:49], v[148:151], v[208:211], v[46:49]
	v_mfma_f32_16x16x32_bf16 v[42:45], v[176:179], v[208:211], v[42:45]
	v_mfma_f32_16x16x32_bf16 v[30:33], v[148:151], v[216:219], v[30:33]
	v_mfma_f32_16x16x32_bf16 v[26:29], v[176:179], v[216:219], v[26:29]
	v_mfma_f32_16x16x32_bf16 v[14:17], v[148:151], v[224:227], v[14:17]
	v_mfma_f32_16x16x32_bf16 v[10:13], v[176:179], v[224:227], v[10:13]
	v_mfma_f32_16x16x32_bf16 v[62:65], v[172:175], v[204:207], v[62:65]
	v_mfma_f32_16x16x32_bf16 v[58:61], v[180:183], v[204:207], v[58:61]
	v_mfma_f32_16x16x32_bf16 v[46:49], v[172:175], v[212:215], v[46:49]
	v_mfma_f32_16x16x32_bf16 v[42:45], v[180:183], v[212:215], v[42:45]
	v_mfma_f32_16x16x32_bf16 v[30:33], v[172:175], v[220:223], v[30:33]
	v_mfma_f32_16x16x32_bf16 v[26:29], v[180:183], v[220:223], v[26:29]
	v_mfma_f32_16x16x32_bf16 v[14:17], v[172:175], v[228:231], v[14:17]
	v_mfma_f32_16x16x32_bf16 v[10:13], v[180:183], v[228:231], v[10:13]
	s_setprio 0
	s_setprio 1
	v_mfma_f32_16x16x32_bf16 v[54:57], v[184:187], v[200:203], v[54:57]
	v_mfma_f32_16x16x32_bf16 v[50:53], v[192:195], v[200:203], v[50:53]
	v_mfma_f32_16x16x32_bf16 v[38:41], v[184:187], v[208:211], v[38:41]
	v_mfma_f32_16x16x32_bf16 v[34:37], v[192:195], v[208:211], v[34:37]
	v_mfma_f32_16x16x32_bf16 v[22:25], v[184:187], v[216:219], v[22:25]
	v_mfma_f32_16x16x32_bf16 v[18:21], v[192:195], v[216:219], v[18:21]
	v_mfma_f32_16x16x32_bf16 v[6:9], v[184:187], v[224:227], v[6:9]
	v_mfma_f32_16x16x32_bf16 v[2:5], v[192:195], v[224:227], v[2:5]
	v_mfma_f32_16x16x32_bf16 v[54:57], v[188:191], v[204:207], v[54:57]
	v_mfma_f32_16x16x32_bf16 v[50:53], v[196:199], v[204:207], v[50:53]
	v_mfma_f32_16x16x32_bf16 v[38:41], v[188:191], v[212:215], v[38:41]
	v_mfma_f32_16x16x32_bf16 v[34:37], v[196:199], v[212:215], v[34:37]
	v_mfma_f32_16x16x32_bf16 v[22:25], v[188:191], v[220:223], v[22:25]
	v_mfma_f32_16x16x32_bf16 v[18:21], v[196:199], v[220:223], v[18:21]
	v_mfma_f32_16x16x32_bf16 v[6:9], v[188:191], v[228:231], v[6:9]
	v_mfma_f32_16x16x32_bf16 v[2:5], v[196:199], v[228:231], v[2:5]
	s_setprio 0
	s_barrier
; #define PG8_STAGE(bufoff, gbase, voff) do { _Pragma("unroll") for (int _i = 0; _i < 2; ++_i) \
;         __builtin_amdgcn_global_load_lds((const unsigned*)((const char*)(gbase) + (voff)[_i]), (PG8_LAS unsigned*)(lds + (bufoff) + ldsw + _i * 8192), 16, 0, 0); } while (0)
; #define PG8_LDA(dst, b, h) do { _Pragma("unroll") for (int m = 0; m < 4; ++m) _Pragma("unroll") for (int k = 0; k < 2; ++k) dst[m][k] = *(const PG8_LAS bf16x8*)(lds + PG8_SA(b, h) + aoff + m * 2048 + k * 1024); } while (0)
; #define PG8_LDB(dst, b, h) do { _Pragma("unroll") for (int n = 0; n < 2; ++n) _Pragma("unroll") for (int k = 0; k < 2; ++k) dst[n][k] = *(const PG8_LAS bf16x8*)(lds + PG8_SB(b, h) + boff + n * 2048 + k * 1024); } while (0)
; #define PG8_MMA(ai, bj, At, Bt) do { __builtin_amdgcn_s_setprio(1); _Pragma("unroll") for (int m = 0; m < 4; ++m) _Pragma("unroll") for (int n = 0; n < 2; ++n) _Pragma("unroll") for (int k = 0; k < 2; ++k) \
;         acc[ai][bj][m][n] = __builtin_amdgcn_mfma_f32_16x16x32_bf16(Bt[n][k], At[m][k], acc[ai][bj][m][n], 0, 0, 0); __builtin_amdgcn_s_setprio(0); } while (0)
; #define PG8_WAIT_V(n) asm volatile("s_waitcnt vmcnt(" #n ")" ::: "memory")
; #define PG8_WAIT_L(n) asm volatile("s_waitcnt lgkmcnt(" #n ")" ::: "memory")
; #define PG8_BAR __builtin_amdgcn_s_barrier()
; #define PG8_SCHED __builtin_amdgcn_sched_barrier(0)
; template <class Epi, class Sched, bool ALIGN_EPI = false, bool SP2 = false, bool KSEG = false>
; __device__ __forceinline__ void gemm_phase(PG8_LAS unsigned char* lds, const Gemm g, const Sched& S, const Epi& E) {
;     ...
;             PG8_LDB(B0, 1, 0); PG8_LDB(B1, 1, 1); PG8_SCHED; PG8_LDA(At, 1, 0); PG8_STAGE(PG8_SA(0, 1), a2 + hstep, voffA);
;             PG8_WAIT_V(8); PG8_WAIT_L(0); PG8_BAR; PG8_MMA(0, 0, At, B0); PG8_MMA(0, 1, At, B1); PG8_BAR; PG8_SCHED;
	s_add_i32 s33, 0, 0x18000
	s_add_i32 s63, 0, 0x1c000
	v_add_u32_e32 v180, s33, v166
	v_add_u32_e32 v196, s63, v166
	ds_read_b128 v[148:151], v180
	ds_read_b128 v[172:175], v180 offset:1024
	ds_read_b128 v[176:179], v180 offset:2048
	ds_read_b128 v[180:183], v180 offset:3072
	ds_read_b128 v[184:187], v196
	ds_read_b128 v[188:191], v196 offset:1024
	ds_read_b128 v[192:195], v196 offset:2048
	ds_read_b128 v[196:199], v196 offset:3072
	ds_read_b128 v[200:203], v170 offset:32768
	ds_read_b128 v[204:207], v170 offset:33792
	ds_read_b128 v[208:211], v170 offset:34816
	ds_read_b128 v[212:215], v170 offset:35840
	ds_read_b128 v[216:219], v170 offset:36864
	ds_read_b128 v[220:223], v170 offset:37888
	ds_read_b128 v[224:227], v170 offset:38912
	ds_read_b128 v[228:231], v170 offset:39936
	s_mov_b32 m0, s31
	v_lshl_add_u64 v[240:241], s[40:41], 0, v[132:133]
	global_load_lds_dwordx4 v[240:241], off
	s_mov_b32 m0, s45
	v_lshl_add_u64 v[240:241], s[40:41], 0, v[136:137]
	global_load_lds_dwordx4 v[240:241], off
	s_add_u32 s40, s40, 0x80000
	s_addc_u32 s41, s41, 0
	s_mov_b32 m0, s49
	v_lshl_add_u64 v[240:241], s[40:41], 0, v[132:133]
	global_load_lds_dwordx4 v[240:241], off
	s_mov_b32 m0, s50
	v_lshl_add_u64 v[240:241], s[40:41], 0, v[136:137]
	global_load_lds_dwordx4 v[240:241], off
	s_waitcnt vmcnt(8) lgkmcnt(0)
	s_barrier
	s_setprio 1
	v_mfma_f32_16x16x32_bf16 v[126:129], v[148:151], v[200:203], v[126:129]
	v_mfma_f32_16x16x32_bf16 v[122:125], v[176:179], v[200:203], v[122:125]
	v_mfma_f32_16x16x32_bf16 v[110:113], v[148:151], v[208:211], v[110:113]
	v_mfma_f32_16x16x32_bf16 v[106:109], v[176:179], v[208:211], v[106:109]
	v_mfma_f32_16x16x32_bf16 v[94:97], v[148:151], v[216:219], v[94:97]
	v_mfma_f32_16x16x32_bf16 v[90:93], v[176:179], v[216:219], v[90:93]
	v_mfma_f32_16x16x32_bf16 v[78:81], v[148:151], v[224:227], v[78:81]
	v_mfma_f32_16x16x32_bf16 v[74:77], v[176:179], v[224:227], v[74:77]
	v_mfma_f32_16x16x32_bf16 v[126:129], v[172:175], v[204:207], v[126:129]
	v_mfma_f32_16x16x32_bf16 v[122:125], v[180:183], v[204:207], v[122:125]
	v_mfma_f32_16x16x32_bf16 v[110:113], v[172:175], v[212:215], v[110:113]
	v_mfma_f32_16x16x32_bf16 v[106:109], v[180:183], v[212:215], v[106:109]
	v_mfma_f32_16x16x32_bf16 v[94:97], v[172:175], v[220:223], v[94:97]
	v_mfma_f32_16x16x32_bf16 v[90:93], v[180:183], v[220:223], v[90:93]
	v_mfma_f32_16x16x32_bf16 v[78:81], v[172:175], v[228:231], v[78:81]
	v_mfma_f32_16x16x32_bf16 v[74:77], v[180:183], v[228:231], v[74:77]
	s_setprio 0
	s_setprio 1
	v_mfma_f32_16x16x32_bf16 v[118:121], v[184:187], v[200:203], v[118:121]
	v_mfma_f32_16x16x32_bf16 v[114:117], v[192:195], v[200:203], v[114:117]
	v_mfma_f32_16x16x32_bf16 v[102:105], v[184:187], v[208:211], v[102:105]
	v_mfma_f32_16x16x32_bf16 v[98:101], v[192:195], v[208:211], v[98:101]
	v_mfma_f32_16x16x32_bf16 v[86:89], v[184:187], v[216:219], v[86:89]
	v_mfma_f32_16x16x32_bf16 v[82:85], v[192:195], v[216:219], v[82:85]
	v_mfma_f32_16x16x32_bf16 v[70:73], v[184:187], v[224:227], v[70:73]
	v_mfma_f32_16x16x32_bf16 v[66:69], v[192:195], v[224:227], v[66:69]
	v_mfma_f32_16x16x32_bf16 v[118:121], v[188:191], v[204:207], v[118:121]
	v_mfma_f32_16x16x32_bf16 v[114:117], v[196:199], v[204:207], v[114:117]
	v_mfma_f32_16x16x32_bf16 v[102:105], v[188:191], v[212:215], v[102:105]
	v_mfma_f32_16x16x32_bf16 v[98:101], v[196:199], v[212:215], v[98:101]
	v_mfma_f32_16x16x32_bf16 v[86:89], v[188:191], v[220:223], v[86:89]
	v_mfma_f32_16x16x32_bf16 v[82:85], v[196:199], v[220:223], v[82:85]
	v_mfma_f32_16x16x32_bf16 v[70:73], v[188:191], v[228:231], v[70:73]
	v_mfma_f32_16x16x32_bf16 v[66:69], v[196:199], v[228:231], v[66:69]
	s_setprio 0
	s_barrier
; #define PG8_STAGE(bufoff, gbase, voff) do { _Pragma("unroll") for (int _i = 0; _i < 2; ++_i) \
;         __builtin_amdgcn_global_load_lds((const unsigned*)((const char*)(gbase) + (voff)[_i]), (PG8_LAS unsigned*)(lds + (bufoff) + ldsw + _i * 8192), 16, 0, 0); } while (0)
; #define PG8_LDA(dst, b, h) do { _Pragma("unroll") for (int m = 0; m < 4; ++m) _Pragma("unroll") for (int k = 0; k < 2; ++k) dst[m][k] = *(const PG8_LAS bf16x8*)(lds + PG8_SA(b, h) + aoff + m * 2048 + k * 1024); } while (0)
; #define PG8_MMA(ai, bj, At, Bt) do { __builtin_amdgcn_s_setprio(1); _Pragma("unroll") for (int m = 0; m < 4; ++m) _Pragma("unroll") for (int n = 0; n < 2; ++n) _Pragma("unroll") for (int k = 0; k < 2; ++k) \
;         acc[ai][bj][m][n] = __builtin_amdgcn_mfma_f32_16x16x32_bf16(Bt[n][k], At[m][k], acc[ai][bj][m][n], 0, 0, 0); __builtin_amdgcn_s_setprio(0); } while (0)
; #define PG8_WAIT_V(n) asm volatile("s_waitcnt vmcnt(" #n ")" ::: "memory")
; #define PG8_WAIT_L(n) asm volatile("s_waitcnt lgkmcnt(" #n ")" ::: "memory")
; #define PG8_BAR __builtin_amdgcn_s_barrier()
; #define PG8_SCHED __builtin_amdgcn_sched_barrier(0)
; template <class Epi, class Sched, bool ALIGN_EPI = false, bool SP2 = false, bool KSEG = false>
; __device__ __forceinline__ void gemm_phase(PG8_LAS unsigned char* lds, const Gemm g, const Sched& S, const Epi& E) {
;     ...
;         for (int t = 0; t < nt; t += 2) {
;             const bool last = (t == nt - 2);
;             const char* a1 = cA + (size_t)(t + 1) * kstep;
;             const char* a2 = last ? nA : cA + (size_t)(t + 2) * kstep; const char* b2 = last ? nB : cB + (size_t)(t + 2) * kstep;
;             const char* a3 = a2 + kstep; const char* b3 = b2 + kstep;
;     ...
;             PG8_LDA(At, 1, 1); PG8_STAGE(PG8_SB(1, 0), b3, voffB); PG8_STAGE(PG8_SB(1, 1), b3 + hstep, voffB); PG8_STAGE(PG8_SA(1, 0), a3, voffA);
;             PG8_WAIT_V(8); PG8_WAIT_L(0); PG8_BAR; PG8_MMA(1, 0, At, B0); PG8_MMA(1, 1, At, B1); PG8_BAR; PG8_SCHED;
	s_add_i32 s33, s33, s43
	v_lshl_add_u64 v[232:233], v[232:233], 0, s[10:11]
	s_mov_b32 m0, s33
	ds_read_b128 v[200:203], v170 offset:49152
	ds_read_b128 v[204:207], v170 offset:50176
	ds_read_b128 v[208:211], v170 offset:51200
	ds_read_b128 v[212:215], v170 offset:52224
	ds_read_b128 v[216:219], v170 offset:53248
	ds_read_b128 v[220:223], v170 offset:54272
	ds_read_b128 v[224:227], v170 offset:55296
	ds_read_b128 v[228:231], v170 offset:56320
	global_load_lds_dwordx4 v[232:233], off
	s_add_i32 m0, s33, 0x2000
	s_add_u32 s38, s38, 0x80080
	v_lshl_add_u64 v[232:233], v[234:235], 0, s[10:11]
	s_addc_u32 s39, s39, 0
	s_add_i32 s33, s63, s43
	global_load_lds_dwordx4 v[232:233], off
	s_mov_b32 m0, s33
	v_lshl_add_u64 v[232:233], s[38:39], 0, v[134:135]
	global_load_lds_dwordx4 v[232:233], off
	s_add_i32 m0, s33, 0x2000
	v_lshl_add_u64 v[232:233], s[38:39], 0, v[138:139]
	global_load_lds_dwordx4 v[232:233], off
	s_waitcnt vmcnt(6) lgkmcnt(0)
	s_barrier
	s_setprio 1
	v_mfma_f32_16x16x32_bf16 v[62:65], v[148:151], v[200:203], v[62:65]
	v_mfma_f32_16x16x32_bf16 v[58:61], v[176:179], v[200:203], v[58:61]
	v_mfma_f32_16x16x32_bf16 v[46:49], v[148:151], v[208:211], v[46:49]
	v_mfma_f32_16x16x32_bf16 v[42:45], v[176:179], v[208:211], v[42:45]
	v_mfma_f32_16x16x32_bf16 v[30:33], v[148:151], v[216:219], v[30:33]
	v_mfma_f32_16x16x32_bf16 v[26:29], v[176:179], v[216:219], v[26:29]
	v_mfma_f32_16x16x32_bf16 v[14:17], v[148:151], v[224:227], v[14:17]
	v_mfma_f32_16x16x32_bf16 v[10:13], v[176:179], v[224:227], v[10:13]
	v_mfma_f32_16x16x32_bf16 v[62:65], v[172:175], v[204:207], v[62:65]
	v_mfma_f32_16x16x32_bf16 v[58:61], v[180:183], v[204:207], v[58:61]
	v_mfma_f32_16x16x32_bf16 v[46:49], v[172:175], v[212:215], v[46:49]
	v_mfma_f32_16x16x32_bf16 v[42:45], v[180:183], v[212:215], v[42:45]
	v_mfma_f32_16x16x32_bf16 v[30:33], v[172:175], v[220:223], v[30:33]
	v_mfma_f32_16x16x32_bf16 v[26:29], v[180:183], v[220:223], v[26:29]
	v_mfma_f32_16x16x32_bf16 v[14:17], v[172:175], v[228:231], v[14:17]
	v_mfma_f32_16x16x32_bf16 v[10:13], v[180:183], v[228:231], v[10:13]
	s_setprio 0
	s_setprio 1
	v_mfma_f32_16x16x32_bf16 v[54:57], v[184:187], v[200:203], v[54:57]
	s_add_i32 s62, s62, 2
	v_mfma_f32_16x16x32_bf16 v[50:53], v[192:195], v[200:203], v[50:53]
	s_add_u32 s36, s36, 0x100
	v_mfma_f32_16x16x32_bf16 v[38:41], v[184:187], v[208:211], v[38:41]
	s_addc_u32 s37, s37, 0
	v_mfma_f32_16x16x32_bf16 v[34:37], v[192:195], v[208:211], v[34:37]
	s_add_u32 s60, s60, 0x100
	v_mfma_f32_16x16x32_bf16 v[22:25], v[184:187], v[216:219], v[22:25]
	s_addc_u32 s61, s61, 0
	v_mfma_f32_16x16x32_bf16 v[18:21], v[192:195], v[216:219], v[18:21]
	s_add_u32 s33, s36, 0xfff80080
	v_mfma_f32_16x16x32_bf16 v[6:9], v[184:187], v[224:227], v[6:9]
	s_addc_u32 s38, s37, -1
	v_mfma_f32_16x16x32_bf16 v[2:5], v[192:195], v[224:227], v[2:5]
	s_cmp_eq_u32 s62, 28
	v_mfma_f32_16x16x32_bf16 v[54:57], v[188:191], v[204:207], v[54:57]
	s_cselect_b32 s41, s25, s38
	v_mfma_f32_16x16x32_bf16 v[50:53], v[196:199], v[204:207], v[50:53]
	s_cselect_b32 s40, s58, s33
	v_mfma_f32_16x16x32_bf16 v[38:41], v[188:191], v[212:215], v[38:41]
	s_cselect_b32 s39, s23, s61
	v_mfma_f32_16x16x32_bf16 v[34:37], v[196:199], v[212:215], v[34:37]
	s_cselect_b32 s38, s59, s60
	v_mfma_f32_16x16x32_bf16 v[22:25], v[188:191], v[220:223], v[22:25]
	s_add_u32 s98, s36, 0xfff80000
	v_mfma_f32_16x16x32_bf16 v[18:21], v[196:199], v[220:223], v[18:21]
	s_addc_u32 s99, s37, -1
	v_mfma_f32_16x16x32_bf16 v[6:9], v[188:191], v[228:231], v[6:9]
	s_cmp_gt_u32 s62, 29
	v_mfma_f32_16x16x32_bf16 v[2:5], v[196:199], v[228:231], v[2:5]
	s_setprio 0
	s_barrier
	s_cbranch_scc0 .LBB0_497
	s_and_b64 vcc, exec, s[12:13]
	s_cbranch_vccz .LBB0_500
	s_barrier

; #define PG8_STAGE(bufoff, gbase, voff) do { _Pragma("unroll") for (int _i = 0; _i < 2; ++_i) \
;         __builtin_amdgcn_global_load_lds((const unsigned*)((const char*)(gbase) + (voff)[_i]), (PG8_LAS unsigned*)(lds + (bufoff) + ldsw + _i * 8192), 16, 0, 0); } while (0)
; #define PG8_LDA(dst, b, h) do { _Pragma("unroll") for (int m = 0; m < 4; ++m) _Pragma("unroll") for (int k = 0; k < 2; ++k) dst[m][k] = *(const PG8_LAS bf16x8*)(lds + PG8_SA(b, h) + aoff + m * 2048 + k * 1024); } while (0)
; #define PG8_LDB(dst, b, h) do { _Pragma("unroll") for (int n = 0; n < 2; ++n) _Pragma("unroll") for (int k = 0; k < 2; ++k) dst[n][k] = *(const PG8_LAS bf16x8*)(lds + PG8_SB(b, h) + boff + n * 2048 + k * 1024); } while (0)
; #define PG8_MMA(ai, bj, At, Bt) do { __builtin_amdgcn_s_setprio(1); _Pragma("unroll") for (int m = 0; m < 4; ++m) _Pragma("unroll") for (int n = 0; n < 2; ++n) _Pragma("unroll") for (int k = 0; k < 2; ++k) \
;         acc[ai][bj][m][n] = __builtin_amdgcn_mfma_f32_16x16x32_bf16(Bt[n][k], At[m][k], acc[ai][bj][m][n], 0, 0, 0); __builtin_amdgcn_s_setprio(0); } while (0)
; #define PG8_WAIT_V(n) asm volatile("s_waitcnt vmcnt(" #n ")" ::: "memory")
; #define PG8_WAIT_L(n) asm volatile("s_waitcnt lgkmcnt(" #n ")" ::: "memory")
; #define PG8_BAR __builtin_amdgcn_s_barrier()
; #define PG8_SCHED __builtin_amdgcn_sched_barrier(0)
; template <class Epi, class Sched, bool ALIGN_EPI = false, bool SP2 = false, bool KSEG = false>
; __device__ __forceinline__ void gemm_phase(PG8_LAS unsigned char* lds, const Gemm g, const Sched& S, const Epi& E) {
;     ...
;             PG8_LDB(B0, 0, 0); PG8_LDB(B1, 0, 1); PG8_SCHED; PG8_LDA(At, 0, 0); PG8_STAGE(PG8_SA(1, 1), a1 + hstep, voffA);
;             PG8_WAIT_V(8); PG8_WAIT_L(0); PG8_BAR; PG8_MMA(0, 0, At, B0); PG8_MMA(0, 1, At, B1); PG8_BAR; PG8_SCHED;
;             PG8_LDA(At, 0, 1); PG8_STAGE(PG8_SB(0, 0), b2, voffB); PG8_STAGE(PG8_SB(0, 1), b2 + hstep, voffB); PG8_STAGE(PG8_SA(0, 0), a2, voffA);
;             PG8_WAIT_V(8); PG8_WAIT_L(0); PG8_BAR; PG8_MMA(1, 0, At, B0); PG8_MMA(1, 1, At, B1); PG8_BAR; PG8_SCHED;
.LBB0_537:
	ds_read_b128 v[154:157], v173
	ds_read_b128 v[176:179], v173 offset:1024
	ds_read_b128 v[180:183], v173 offset:2048
	ds_read_b128 v[184:187], v173 offset:3072
	ds_read_b128 v[188:191], v174
	ds_read_b128 v[192:195], v174 offset:1024
	ds_read_b128 v[196:199], v174 offset:2048
	ds_read_b128 v[200:203], v174 offset:3072
	ds_read_b128 v[204:207], v175
	ds_read_b128 v[208:211], v175 offset:1024
	ds_read_b128 v[212:215], v175 offset:2048
	ds_read_b128 v[216:219], v175 offset:3072
	ds_read_b128 v[220:223], v175 offset:4096
	ds_read_b128 v[224:227], v175 offset:5120
	ds_read_b128 v[228:231], v175 offset:6144
	ds_read_b128 v[232:235], v175 offset:7168
	s_mov_b32 m0, s54
	v_lshl_add_u64 v[236:237], s[98:99], 0, v[140:141]
	global_load_lds_dwordx4 v[236:237], off
	s_mov_b32 m0, s55
	v_lshl_add_u64 v[236:237], s[98:99], 0, v[142:143]
	global_load_lds_dwordx4 v[236:237], off
	v_lshl_add_u64 v[236:237], s[36:37], 0, v[146:147]
	s_add_i32 m0, s44, 0xc000
	s_nop 0
	global_load_lds_dwordx4 v[236:237], off
	s_add_i32 m0, s44, 0xe000
	v_lshl_add_u64 v[236:237], s[36:37], 0, v[148:149]
	global_load_lds_dwordx4 v[236:237], off
	s_waitcnt vmcnt(8) lgkmcnt(0)
	s_barrier
	s_setprio 1
	v_mfma_f32_16x16x32_bf16 v[126:129], v[154:157], v[204:207], v[126:129]
	v_mfma_f32_16x16x32_bf16 v[122:125], v[180:183], v[204:207], v[122:125]
	v_mfma_f32_16x16x32_bf16 v[110:113], v[154:157], v[212:215], v[110:113]
	v_mfma_f32_16x16x32_bf16 v[106:109], v[180:183], v[212:215], v[106:109]
	v_mfma_f32_16x16x32_bf16 v[94:97], v[154:157], v[220:223], v[94:97]
	v_mfma_f32_16x16x32_bf16 v[90:93], v[180:183], v[220:223], v[90:93]
	v_mfma_f32_16x16x32_bf16 v[78:81], v[154:157], v[228:231], v[78:81]
	v_mfma_f32_16x16x32_bf16 v[74:77], v[180:183], v[228:231], v[74:77]
	v_mfma_f32_16x16x32_bf16 v[126:129], v[176:179], v[208:211], v[126:129]
	v_mfma_f32_16x16x32_bf16 v[122:125], v[184:187], v[208:211], v[122:125]
	v_mfma_f32_16x16x32_bf16 v[110:113], v[176:179], v[216:219], v[110:113]
	v_mfma_f32_16x16x32_bf16 v[106:109], v[184:187], v[216:219], v[106:109]
	v_mfma_f32_16x16x32_bf16 v[94:97], v[176:179], v[224:227], v[94:97]
	v_mfma_f32_16x16x32_bf16 v[90:93], v[184:187], v[224:227], v[90:93]
	v_mfma_f32_16x16x32_bf16 v[78:81], v[176:179], v[232:235], v[78:81]
	v_mfma_f32_16x16x32_bf16 v[74:77], v[184:187], v[232:235], v[74:77]
	s_setprio 0
	s_setprio 1
	v_mfma_f32_16x16x32_bf16 v[118:121], v[188:191], v[204:207], v[118:121]
	v_mfma_f32_16x16x32_bf16 v[114:117], v[196:199], v[204:207], v[114:117]
	v_mfma_f32_16x16x32_bf16 v[102:105], v[188:191], v[212:215], v[102:105]
	v_mfma_f32_16x16x32_bf16 v[98:101], v[196:199], v[212:215], v[98:101]
	v_mfma_f32_16x16x32_bf16 v[86:89], v[188:191], v[220:223], v[86:89]
	v_mfma_f32_16x16x32_bf16 v[82:85], v[196:199], v[220:223], v[82:85]
	v_mfma_f32_16x16x32_bf16 v[70:73], v[188:191], v[228:231], v[70:73]
	v_mfma_f32_16x16x32_bf16 v[66:69], v[196:199], v[228:231], v[66:69]
	v_mfma_f32_16x16x32_bf16 v[118:121], v[192:195], v[208:211], v[118:121]
	v_mfma_f32_16x16x32_bf16 v[114:117], v[200:203], v[208:211], v[114:117]
	v_mfma_f32_16x16x32_bf16 v[102:105], v[192:195], v[216:219], v[102:105]
	v_mfma_f32_16x16x32_bf16 v[98:101], v[200:203], v[216:219], v[98:101]
	v_mfma_f32_16x16x32_bf16 v[86:89], v[192:195], v[224:227], v[86:89]
	v_mfma_f32_16x16x32_bf16 v[82:85], v[200:203], v[224:227], v[82:85]
	v_mfma_f32_16x16x32_bf16 v[70:73], v[192:195], v[232:235], v[70:73]
	v_mfma_f32_16x16x32_bf16 v[66:69], v[200:203], v[232:235], v[66:69]
	s_setprio 0
	s_barrier
	s_add_i32 s33, s56, s43
	v_lshl_add_u64 v[236:237], s[38:39], 0, v[130:131]
	s_mov_b32 m0, s33
	ds_read_b128 v[204:207], v175 offset:16384
	ds_read_b128 v[208:211], v175 offset:17408
	ds_read_b128 v[212:215], v175 offset:18432
	ds_read_b128 v[216:219], v175 offset:19456
	ds_read_b128 v[220:223], v175 offset:20480
	ds_read_b128 v[224:227], v175 offset:21504
	ds_read_b128 v[228:231], v175 offset:22528
	ds_read_b128 v[232:235], v175 offset:23552
	global_load_lds_dwordx4 v[236:237], off
	s_add_i32 m0, s33, 0x2000
	s_add_u32 s66, s38, 0x160000
	v_lshl_add_u64 v[238:239], s[38:39], 0, v[144:145]
	s_addc_u32 s67, s39, 0
	s_add_i32 s33, s57, s43
	global_load_lds_dwordx4 v[238:239], off
	s_mov_b32 m0, s33
	v_lshl_add_u64 v[240:241], s[66:67], 0, v[130:131]
	global_load_lds_dwordx4 v[240:241], off
	s_add_i32 m0, s33, 0x2000
	v_lshl_add_u64 v[240:241], s[66:67], 0, v[144:145]
	global_load_lds_dwordx4 v[240:241], off
	s_waitcnt vmcnt(6) lgkmcnt(0)
	s_barrier
	s_setprio 1
	v_mfma_f32_16x16x32_bf16 v[62:65], v[154:157], v[204:207], v[62:65]
	v_mfma_f32_16x16x32_bf16 v[58:61], v[180:183], v[204:207], v[58:61]
	v_mfma_f32_16x16x32_bf16 v[46:49], v[154:157], v[212:215], v[46:49]
	v_mfma_f32_16x16x32_bf16 v[42:45], v[180:183], v[212:215], v[42:45]
	v_mfma_f32_16x16x32_bf16 v[30:33], v[154:157], v[220:223], v[30:33]
	v_mfma_f32_16x16x32_bf16 v[26:29], v[180:183], v[220:223], v[26:29]
	v_mfma_f32_16x16x32_bf16 v[14:17], v[154:157], v[228:231], v[14:17]
	v_mfma_f32_16x16x32_bf16 v[10:13], v[180:183], v[228:231], v[10:13]
	v_mfma_f32_16x16x32_bf16 v[62:65], v[176:179], v[208:211], v[62:65]
	v_mfma_f32_16x16x32_bf16 v[58:61], v[184:187], v[208:211], v[58:61]
	v_mfma_f32_16x16x32_bf16 v[46:49], v[176:179], v[216:219], v[46:49]
	v_mfma_f32_16x16x32_bf16 v[42:45], v[184:187], v[216:219], v[42:45]
	v_mfma_f32_16x16x32_bf16 v[30:33], v[176:179], v[224:227], v[30:33]
	v_mfma_f32_16x16x32_bf16 v[26:29], v[184:187], v[224:227], v[26:29]
	v_mfma_f32_16x16x32_bf16 v[14:17], v[176:179], v[232:235], v[14:17]
	v_mfma_f32_16x16x32_bf16 v[10:13], v[184:187], v[232:235], v[10:13]
	s_setprio 0
	s_setprio 1
	v_mfma_f32_16x16x32_bf16 v[54:57], v[188:191], v[204:207], v[54:57]
	v_mfma_f32_16x16x32_bf16 v[50:53], v[196:199], v[204:207], v[50:53]
	v_mfma_f32_16x16x32_bf16 v[38:41], v[188:191], v[212:215], v[38:41]
	v_mfma_f32_16x16x32_bf16 v[34:37], v[196:199], v[212:215], v[34:37]
	v_mfma_f32_16x16x32_bf16 v[22:25], v[188:191], v[220:223], v[22:25]
	v_mfma_f32_16x16x32_bf16 v[18:21], v[196:199], v[220:223], v[18:21]
	v_mfma_f32_16x16x32_bf16 v[6:9], v[188:191], v[228:231], v[6:9]
	v_mfma_f32_16x16x32_bf16 v[2:5], v[196:199], v[228:231], v[2:5]
	v_mfma_f32_16x16x32_bf16 v[54:57], v[192:195], v[208:211], v[54:57]
	v_mfma_f32_16x16x32_bf16 v[50:53], v[200:203], v[208:211], v[50:53]
	v_mfma_f32_16x16x32_bf16 v[38:41], v[192:195], v[216:219], v[38:41]
	v_mfma_f32_16x16x32_bf16 v[34:37], v[200:203], v[216:219], v[34:37]
	v_mfma_f32_16x16x32_bf16 v[22:25], v[192:195], v[224:227], v[22:25]
	v_mfma_f32_16x16x32_bf16 v[18:21], v[200:203], v[224:227], v[18:21]
	v_mfma_f32_16x16x32_bf16 v[6:9], v[192:195], v[232:235], v[6:9]
	v_mfma_f32_16x16x32_bf16 v[2:5], v[200:203], v[232:235], v[2:5]
	s_setprio 0
	s_barrier
; #define PG8_STAGE(bufoff, gbase, voff) do { _Pragma("unroll") for (int _i = 0; _i < 2; ++_i) \
;         __builtin_amdgcn_global_load_lds((const unsigned*)((const char*)(gbase) + (voff)[_i]), (PG8_LAS unsigned*)(lds + (bufoff) + ldsw + _i * 8192), 16, 0, 0); } while (0)
; #define PG8_LDA(dst, b, h) do { _Pragma("unroll") for (int m = 0; m < 4; ++m) _Pragma("unroll") for (int k = 0; k < 2; ++k) dst[m][k] = *(const PG8_LAS bf16x8*)(lds + PG8_SA(b, h) + aoff + m * 2048 + k * 1024); } while (0)
; #define PG8_LDB(dst, b, h) do { _Pragma("unroll") for (int n = 0; n < 2; ++n) _Pragma("unroll") for (int k = 0; k < 2; ++k) dst[n][k] = *(const PG8_LAS bf16x8*)(lds + PG8_SB(b, h) + boff + n * 2048 + k * 1024); } while (0)
; #define PG8_MMA(ai, bj, At, Bt) do { __builtin_amdgcn_s_setprio(1); _Pragma("unroll") for (int m = 0; m < 4; ++m) _Pragma("unroll") for (int n = 0; n < 2; ++n) _Pragma("unroll") for (int k = 0; k < 2; ++k) \
;         acc[ai][bj][m][n] = __builtin_amdgcn_mfma_f32_16x16x32_bf16(Bt[n][k], At[m][k], acc[ai][bj][m][n], 0, 0, 0); __builtin_amdgcn_s_setprio(0); } while (0)
; #define PG8_WAIT_V(n) asm volatile("s_waitcnt vmcnt(" #n ")" ::: "memory")
; #define PG8_WAIT_L(n) asm volatile("s_waitcnt lgkmcnt(" #n ")" ::: "memory")
; #define PG8_BAR __builtin_amdgcn_s_barrier()
; #define PG8_SCHED __builtin_amdgcn_sched_barrier(0)
; template <class Epi, class Sched, bool ALIGN_EPI = false, bool SP2 = false, bool KSEG = false>
; __device__ __forceinline__ void gemm_phase(PG8_LAS unsigned char* lds, const Gemm g, const Sched& S, const Epi& E) {
;     ...
;             PG8_LDB(B0, 1, 0); PG8_LDB(B1, 1, 1); PG8_SCHED; PG8_LDA(At, 1, 0); PG8_STAGE(PG8_SA(0, 1), a2 + hstep, voffA);
;             PG8_WAIT_V(8); PG8_WAIT_L(0); PG8_BAR; PG8_MMA(0, 0, At, B0); PG8_MMA(0, 1, At, B1); PG8_BAR; PG8_SCHED;
	s_add_i32 s33, 0, 0x18000
	s_add_i32 s65, 0, 0x1c000
	v_add_u32_e32 v184, s33, v171
	v_add_u32_e32 v200, s65, v171
	ds_read_b128 v[154:157], v184
	ds_read_b128 v[176:179], v184 offset:1024
	ds_read_b128 v[180:183], v184 offset:2048
	ds_read_b128 v[184:187], v184 offset:3072
	ds_read_b128 v[188:191], v200
	ds_read_b128 v[192:195], v200 offset:1024
	ds_read_b128 v[196:199], v200 offset:2048
	ds_read_b128 v[200:203], v200 offset:3072
	ds_read_b128 v[204:207], v175 offset:32768
	ds_read_b128 v[208:211], v175 offset:33792
	ds_read_b128 v[212:215], v175 offset:34816
	ds_read_b128 v[216:219], v175 offset:35840
	ds_read_b128 v[220:223], v175 offset:36864
	ds_read_b128 v[224:227], v175 offset:37888
	ds_read_b128 v[228:231], v175 offset:38912
	ds_read_b128 v[232:235], v175 offset:39936
	s_mov_b32 m0, s44
	v_lshl_add_u64 v[244:245], s[40:41], 0, v[140:141]
	global_load_lds_dwordx4 v[244:245], off
	s_mov_b32 m0, s45
	v_lshl_add_u64 v[244:245], s[40:41], 0, v[142:143]
	global_load_lds_dwordx4 v[244:245], off
	s_add_u32 s40, s40, 0x160000
	s_addc_u32 s41, s41, 0
	s_mov_b32 m0, s51
	v_lshl_add_u64 v[244:245], s[40:41], 0, v[140:141]
	global_load_lds_dwordx4 v[244:245], off
	s_mov_b32 m0, s52
	v_lshl_add_u64 v[244:245], s[40:41], 0, v[142:143]
	global_load_lds_dwordx4 v[244:245], off
	s_waitcnt vmcnt(8) lgkmcnt(0)
	s_barrier
	s_setprio 1
	v_mfma_f32_16x16x32_bf16 v[126:129], v[154:157], v[204:207], v[126:129]
	v_mfma_f32_16x16x32_bf16 v[122:125], v[180:183], v[204:207], v[122:125]
	v_mfma_f32_16x16x32_bf16 v[110:113], v[154:157], v[212:215], v[110:113]
	v_mfma_f32_16x16x32_bf16 v[106:109], v[180:183], v[212:215], v[106:109]
	v_mfma_f32_16x16x32_bf16 v[94:97], v[154:157], v[220:223], v[94:97]
	v_mfma_f32_16x16x32_bf16 v[90:93], v[180:183], v[220:223], v[90:93]
	v_mfma_f32_16x16x32_bf16 v[78:81], v[154:157], v[228:231], v[78:81]
	v_mfma_f32_16x16x32_bf16 v[74:77], v[180:183], v[228:231], v[74:77]
	v_mfma_f32_16x16x32_bf16 v[126:129], v[176:179], v[208:211], v[126:129]
	v_mfma_f32_16x16x32_bf16 v[122:125], v[184:187], v[208:211], v[122:125]
	v_mfma_f32_16x16x32_bf16 v[110:113], v[176:179], v[216:219], v[110:113]
	v_mfma_f32_16x16x32_bf16 v[106:109], v[184:187], v[216:219], v[106:109]
	v_mfma_f32_16x16x32_bf16 v[94:97], v[176:179], v[224:227], v[94:97]
	v_mfma_f32_16x16x32_bf16 v[90:93], v[184:187], v[224:227], v[90:93]
	v_mfma_f32_16x16x32_bf16 v[78:81], v[176:179], v[232:235], v[78:81]
	v_mfma_f32_16x16x32_bf16 v[74:77], v[184:187], v[232:235], v[74:77]
	s_setprio 0
	s_setprio 1
	v_mfma_f32_16x16x32_bf16 v[118:121], v[188:191], v[204:207], v[118:121]
	v_mfma_f32_16x16x32_bf16 v[114:117], v[196:199], v[204:207], v[114:117]
	v_mfma_f32_16x16x32_bf16 v[102:105], v[188:191], v[212:215], v[102:105]
	v_mfma_f32_16x16x32_bf16 v[98:101], v[196:199], v[212:215], v[98:101]
	v_mfma_f32_16x16x32_bf16 v[86:89], v[188:191], v[220:223], v[86:89]
	v_mfma_f32_16x16x32_bf16 v[82:85], v[196:199], v[220:223], v[82:85]
	v_mfma_f32_16x16x32_bf16 v[70:73], v[188:191], v[228:231], v[70:73]
	v_mfma_f32_16x16x32_bf16 v[66:69], v[196:199], v[228:231], v[66:69]
	v_mfma_f32_16x16x32_bf16 v[118:121], v[192:195], v[208:211], v[118:121]
	v_mfma_f32_16x16x32_bf16 v[114:117], v[200:203], v[208:211], v[114:117]
	v_mfma_f32_16x16x32_bf16 v[102:105], v[192:195], v[216:219], v[102:105]
	v_mfma_f32_16x16x32_bf16 v[98:101], v[200:203], v[216:219], v[98:101]
	v_mfma_f32_16x16x32_bf16 v[86:89], v[192:195], v[224:227], v[86:89]
	v_mfma_f32_16x16x32_bf16 v[82:85], v[200:203], v[224:227], v[82:85]
	v_mfma_f32_16x16x32_bf16 v[70:73], v[192:195], v[232:235], v[70:73]
	v_mfma_f32_16x16x32_bf16 v[66:69], v[200:203], v[232:235], v[66:69]
	s_setprio 0
	s_barrier
; #define PG8_STAGE(bufoff, gbase, voff) do { _Pragma("unroll") for (int _i = 0; _i < 2; ++_i) \
;         __builtin_amdgcn_global_load_lds((const unsigned*)((const char*)(gbase) + (voff)[_i]), (PG8_LAS unsigned*)(lds + (bufoff) + ldsw + _i * 8192), 16, 0, 0); } while (0)
; #define PG8_LDA(dst, b, h) do { _Pragma("unroll") for (int m = 0; m < 4; ++m) _Pragma("unroll") for (int k = 0; k < 2; ++k) dst[m][k] = *(const PG8_LAS bf16x8*)(lds + PG8_SA(b, h) + aoff + m * 2048 + k * 1024); } while (0)
; #define PG8_MMA(ai, bj, At, Bt) do { __builtin_amdgcn_s_setprio(1); _Pragma("unroll") for (int m = 0; m < 4; ++m) _Pragma("unroll") for (int n = 0; n < 2; ++n) _Pragma("unroll") for (int k = 0; k < 2; ++k) \
;         acc[ai][bj][m][n] = __builtin_amdgcn_mfma_f32_16x16x32_bf16(Bt[n][k], At[m][k], acc[ai][bj][m][n], 0, 0, 0); __builtin_amdgcn_s_setprio(0); } while (0)
; #define PG8_WAIT_V(n) asm volatile("s_waitcnt vmcnt(" #n ")" ::: "memory")
; #define PG8_WAIT_L(n) asm volatile("s_waitcnt lgkmcnt(" #n ")" ::: "memory")
; #define PG8_BAR __builtin_amdgcn_s_barrier()
; #define PG8_SCHED __builtin_amdgcn_sched_barrier(0)
; template <class Epi, class Sched, bool ALIGN_EPI = false, bool SP2 = false, bool KSEG = false>
; __device__ __forceinline__ void gemm_phase(PG8_LAS unsigned char* lds, const Gemm g, const Sched& S, const Epi& E) {
;     ...
;         for (int t = 0; t < nt; t += 2) {
;             const bool last = (t == nt - 2);
;             const char* a1 = cA + (size_t)(t + 1) * kstep;
;             const char* a2 = last ? nA : cA + (size_t)(t + 2) * kstep; const char* b2 = last ? nB : cB + (size_t)(t + 2) * kstep;
;             const char* a3 = a2 + kstep; const char* b3 = b2 + kstep;
;     ...
;             PG8_LDA(At, 1, 1); PG8_STAGE(PG8_SB(1, 0), b3, voffB); PG8_STAGE(PG8_SB(1, 1), b3 + hstep, voffB); PG8_STAGE(PG8_SA(1, 0), a3, voffA);
;             PG8_WAIT_V(8); PG8_WAIT_L(0); PG8_BAR; PG8_MMA(1, 0, At, B0); PG8_MMA(1, 1, At, B1); PG8_BAR; PG8_SCHED;
	s_add_i32 s33, s33, s43
	v_lshl_add_u64 v[236:237], v[236:237], 0, s[26:27]
	s_mov_b32 m0, s33
	ds_read_b128 v[204:207], v175 offset:49152
	ds_read_b128 v[208:211], v175 offset:50176
	ds_read_b128 v[212:215], v175 offset:51200
	ds_read_b128 v[216:219], v175 offset:52224
	ds_read_b128 v[220:223], v175 offset:53248
	ds_read_b128 v[224:227], v175 offset:54272
	ds_read_b128 v[228:231], v175 offset:55296
	ds_read_b128 v[232:235], v175 offset:56320
	global_load_lds_dwordx4 v[236:237], off
	s_add_i32 m0, s33, 0x2000
	s_add_u32 s38, s38, 0x160080
	v_lshl_add_u64 v[236:237], v[238:239], 0, s[26:27]
	s_addc_u32 s39, s39, 0
	s_add_i32 s33, s65, s43
	global_load_lds_dwordx4 v[236:237], off
	s_mov_b32 m0, s33
	v_lshl_add_u64 v[236:237], s[38:39], 0, v[130:131]
	global_load_lds_dwordx4 v[236:237], off
	s_add_i32 m0, s33, 0x2000
	v_lshl_add_u64 v[236:237], s[38:39], 0, v[144:145]
	global_load_lds_dwordx4 v[236:237], off
	s_waitcnt vmcnt(6) lgkmcnt(0)
	s_barrier
	s_setprio 1
	v_mfma_f32_16x16x32_bf16 v[62:65], v[154:157], v[204:207], v[62:65]
	v_mfma_f32_16x16x32_bf16 v[58:61], v[180:183], v[204:207], v[58:61]
	v_mfma_f32_16x16x32_bf16 v[46:49], v[154:157], v[212:215], v[46:49]
	v_mfma_f32_16x16x32_bf16 v[42:45], v[180:183], v[212:215], v[42:45]
	v_mfma_f32_16x16x32_bf16 v[30:33], v[154:157], v[220:223], v[30:33]
	v_mfma_f32_16x16x32_bf16 v[26:29], v[180:183], v[220:223], v[26:29]
	v_mfma_f32_16x16x32_bf16 v[14:17], v[154:157], v[228:231], v[14:17]
	v_mfma_f32_16x16x32_bf16 v[10:13], v[180:183], v[228:231], v[10:13]
	v_mfma_f32_16x16x32_bf16 v[62:65], v[176:179], v[208:211], v[62:65]
	v_mfma_f32_16x16x32_bf16 v[58:61], v[184:187], v[208:211], v[58:61]
	v_mfma_f32_16x16x32_bf16 v[46:49], v[176:179], v[216:219], v[46:49]
	v_mfma_f32_16x16x32_bf16 v[42:45], v[184:187], v[216:219], v[42:45]
	v_mfma_f32_16x16x32_bf16 v[30:33], v[176:179], v[224:227], v[30:33]
	v_mfma_f32_16x16x32_bf16 v[26:29], v[184:187], v[224:227], v[26:29]
	v_mfma_f32_16x16x32_bf16 v[14:17], v[176:179], v[232:235], v[14:17]
	v_mfma_f32_16x16x32_bf16 v[10:13], v[184:187], v[232:235], v[10:13]
	s_setprio 0
	s_setprio 1
	v_mfma_f32_16x16x32_bf16 v[54:57], v[188:191], v[204:207], v[54:57]
	s_add_i32 s64, s64, 2
	v_mfma_f32_16x16x32_bf16 v[50:53], v[196:199], v[204:207], v[50:53]
	s_add_u32 s36, s36, 0x100
	v_mfma_f32_16x16x32_bf16 v[38:41], v[188:191], v[212:215], v[38:41]
	s_addc_u32 s37, s37, 0
	v_mfma_f32_16x16x32_bf16 v[34:37], v[196:199], v[212:215], v[34:37]
	s_add_u32 s62, s62, 0x100
	v_mfma_f32_16x16x32_bf16 v[22:25], v[188:191], v[220:223], v[22:25]
	s_addc_u32 s63, s63, 0
	v_mfma_f32_16x16x32_bf16 v[18:21], v[196:199], v[220:223], v[18:21]
	s_add_u32 s33, s36, 0xffea0080
	v_mfma_f32_16x16x32_bf16 v[6:9], v[188:191], v[228:231], v[6:9]
	s_addc_u32 s38, s37, -1
	v_mfma_f32_16x16x32_bf16 v[2:5], v[196:199], v[228:231], v[2:5]
	s_cmpk_eq_i32 s64, 0x54
	v_mfma_f32_16x16x32_bf16 v[54:57], v[192:195], v[208:211], v[54:57]
	s_cselect_b32 s41, s13, s38
	v_mfma_f32_16x16x32_bf16 v[50:53], v[200:203], v[208:211], v[50:53]
	s_cselect_b32 s40, s12, s33
	v_mfma_f32_16x16x32_bf16 v[38:41], v[192:195], v[216:219], v[38:41]
	s_cselect_b32 s39, s31, s63
	v_mfma_f32_16x16x32_bf16 v[34:37], v[200:203], v[216:219], v[34:37]
	s_cselect_b32 s38, s30, s62
	v_mfma_f32_16x16x32_bf16 v[22:25], v[192:195], v[224:227], v[22:25]
	s_add_u32 s98, s36, 0xffea0000
	v_mfma_f32_16x16x32_bf16 v[18:21], v[200:203], v[224:227], v[18:21]
	s_addc_u32 s99, s37, -1
	v_mfma_f32_16x16x32_bf16 v[6:9], v[192:195], v[232:235], v[6:9]
	s_cmpk_gt_u32 s64, 0x55
	v_mfma_f32_16x16x32_bf16 v[2:5], v[200:203], v[232:235], v[2:5]
	s_setprio 0
	s_barrier
	s_cbranch_scc0 .LBB0_537
	s_and_b64 vcc, exec, s[28:29]
	s_cbranch_vccz .LBB0_540
	s_barrier

; #define PG8_STAGE(bufoff, gbase, voff) do { _Pragma("unroll") for (int _i = 0; _i < 2; ++_i) \
;         __builtin_amdgcn_global_load_lds((const unsigned*)((const char*)(gbase) + (voff)[_i]), (PG8_LAS unsigned*)(lds + (bufoff) + ldsw + _i * 8192), 16, 0, 0); } while (0)
; #define PG8_LDA(dst, b, h) do { _Pragma("unroll") for (int m = 0; m < 4; ++m) _Pragma("unroll") for (int k = 0; k < 2; ++k) dst[m][k] = *(const PG8_LAS bf16x8*)(lds + PG8_SA(b, h) + aoff + m * 2048 + k * 1024); } while (0)
; #define PG8_LDB(dst, b, h) do { _Pragma("unroll") for (int n = 0; n < 2; ++n) _Pragma("unroll") for (int k = 0; k < 2; ++k) dst[n][k] = *(const PG8_LAS bf16x8*)(lds + PG8_SB(b, h) + boff + n * 2048 + k * 1024); } while (0)
; #define PG8_MMA(ai, bj, At, Bt) do { __builtin_amdgcn_s_setprio(1); _Pragma("unroll") for (int m = 0; m < 4; ++m) _Pragma("unroll") for (int n = 0; n < 2; ++n) _Pragma("unroll") for (int k = 0; k < 2; ++k) \
;         acc[ai][bj][m][n] = __builtin_amdgcn_mfma_f32_16x16x32_bf16(Bt[n][k], At[m][k], acc[ai][bj][m][n], 0, 0, 0); __builtin_amdgcn_s_setprio(0); } while (0)
; #define PG8_WAIT_V(n) asm volatile("s_waitcnt vmcnt(" #n ")" ::: "memory")
; #define PG8_WAIT_L(n) asm volatile("s_waitcnt lgkmcnt(" #n ")" ::: "memory")
; #define PG8_BAR __builtin_amdgcn_s_barrier()
; #define PG8_SCHED __builtin_amdgcn_sched_barrier(0)
; template <class Epi, class Sched, bool ALIGN_EPI = false, bool SP2 = false, bool KSEG = false>
; __device__ __forceinline__ void gemm_phase(PG8_LAS unsigned char* lds, const Gemm g, const Sched& S, const Epi& E) {
;     ...
;             PG8_LDB(B0, 0, 0); PG8_LDB(B1, 0, 1); PG8_SCHED; PG8_LDA(At, 0, 0); PG8_STAGE(PG8_SA(1, 1), a1 + hstep, voffA);
;             PG8_WAIT_V(8); PG8_WAIT_L(0); PG8_BAR; PG8_MMA(0, 0, At, B0); PG8_MMA(0, 1, At, B1); PG8_BAR; PG8_SCHED;
;             PG8_LDA(At, 0, 1); PG8_STAGE(PG8_SB(0, 0), b2, voffB); PG8_STAGE(PG8_SB(0, 1), b2 + hstep, voffB); PG8_STAGE(PG8_SA(0, 0), a2, voffA);
;             PG8_WAIT_V(8); PG8_WAIT_L(0); PG8_BAR; PG8_MMA(1, 0, At, B0); PG8_MMA(1, 1, At, B1); PG8_BAR; PG8_SCHED;
.LBB0_581:
	ds_read_b128 v[154:157], v160
	ds_read_b128 v[172:175], v160 offset:1024
	ds_read_b128 v[176:179], v160 offset:2048
	ds_read_b128 v[180:183], v160 offset:3072
	ds_read_b128 v[184:187], v161
	ds_read_b128 v[188:191], v161 offset:1024
	ds_read_b128 v[192:195], v161 offset:2048
	ds_read_b128 v[196:199], v161 offset:3072
	ds_read_b128 v[200:203], v164
	ds_read_b128 v[204:207], v164 offset:1024
	ds_read_b128 v[208:211], v164 offset:2048
	ds_read_b128 v[212:215], v164 offset:3072
	ds_read_b128 v[216:219], v164 offset:4096
	ds_read_b128 v[220:223], v164 offset:5120
	ds_read_b128 v[224:227], v164 offset:6144
	ds_read_b128 v[228:231], v164 offset:7168
	s_mov_b32 m0, s60
	v_lshl_add_u64 v[232:233], s[98:99], 0, v[132:133]
	global_load_lds_dwordx4 v[232:233], off
	s_mov_b32 m0, s61
	v_lshl_add_u64 v[232:233], s[98:99], 0, v[136:137]
	global_load_lds_dwordx4 v[232:233], off
	v_lshl_add_u64 v[232:233], s[40:41], 0, v[146:147]
	s_add_i32 m0, s55, 0xc000
	s_nop 0
	global_load_lds_dwordx4 v[232:233], off
	s_add_i32 m0, s55, 0xe000
	v_lshl_add_u64 v[232:233], s[40:41], 0, v[148:149]
	global_load_lds_dwordx4 v[232:233], off
	s_waitcnt vmcnt(8) lgkmcnt(0)
	s_barrier
	s_setprio 1
	v_mfma_f32_16x16x32_bf16 v[126:129], v[154:157], v[200:203], v[126:129]
	v_mfma_f32_16x16x32_bf16 v[122:125], v[176:179], v[200:203], v[122:125]
	v_mfma_f32_16x16x32_bf16 v[110:113], v[154:157], v[208:211], v[110:113]
	v_mfma_f32_16x16x32_bf16 v[106:109], v[176:179], v[208:211], v[106:109]
	v_mfma_f32_16x16x32_bf16 v[94:97], v[154:157], v[216:219], v[94:97]
	v_mfma_f32_16x16x32_bf16 v[90:93], v[176:179], v[216:219], v[90:93]
	v_mfma_f32_16x16x32_bf16 v[78:81], v[154:157], v[224:227], v[78:81]
	v_mfma_f32_16x16x32_bf16 v[74:77], v[176:179], v[224:227], v[74:77]
	v_mfma_f32_16x16x32_bf16 v[126:129], v[172:175], v[204:207], v[126:129]
	v_mfma_f32_16x16x32_bf16 v[122:125], v[180:183], v[204:207], v[122:125]
	v_mfma_f32_16x16x32_bf16 v[110:113], v[172:175], v[212:215], v[110:113]
	v_mfma_f32_16x16x32_bf16 v[106:109], v[180:183], v[212:215], v[106:109]
	v_mfma_f32_16x16x32_bf16 v[94:97], v[172:175], v[220:223], v[94:97]
	v_mfma_f32_16x16x32_bf16 v[90:93], v[180:183], v[220:223], v[90:93]
	v_mfma_f32_16x16x32_bf16 v[78:81], v[172:175], v[228:231], v[78:81]
	v_mfma_f32_16x16x32_bf16 v[74:77], v[180:183], v[228:231], v[74:77]
	s_setprio 0
	s_setprio 1
	v_mfma_f32_16x16x32_bf16 v[118:121], v[184:187], v[200:203], v[118:121]
	v_mfma_f32_16x16x32_bf16 v[114:117], v[192:195], v[200:203], v[114:117]
	v_mfma_f32_16x16x32_bf16 v[102:105], v[184:187], v[208:211], v[102:105]
	v_mfma_f32_16x16x32_bf16 v[98:101], v[192:195], v[208:211], v[98:101]
	v_mfma_f32_16x16x32_bf16 v[86:89], v[184:187], v[216:219], v[86:89]
	v_mfma_f32_16x16x32_bf16 v[82:85], v[192:195], v[216:219], v[82:85]
	v_mfma_f32_16x16x32_bf16 v[70:73], v[184:187], v[224:227], v[70:73]
	v_mfma_f32_16x16x32_bf16 v[66:69], v[192:195], v[224:227], v[66:69]
	v_mfma_f32_16x16x32_bf16 v[118:121], v[188:191], v[204:207], v[118:121]
	v_mfma_f32_16x16x32_bf16 v[114:117], v[196:199], v[204:207], v[114:117]
	v_mfma_f32_16x16x32_bf16 v[102:105], v[188:191], v[212:215], v[102:105]
	v_mfma_f32_16x16x32_bf16 v[98:101], v[196:199], v[212:215], v[98:101]
	v_mfma_f32_16x16x32_bf16 v[86:89], v[188:191], v[220:223], v[86:89]
	v_mfma_f32_16x16x32_bf16 v[82:85], v[196:199], v[220:223], v[82:85]
	v_mfma_f32_16x16x32_bf16 v[70:73], v[188:191], v[228:231], v[70:73]
	v_mfma_f32_16x16x32_bf16 v[66:69], v[196:199], v[228:231], v[66:69]
	s_setprio 0
	s_barrier
	s_add_i32 s33, s62, s53
	v_lshl_add_u64 v[232:233], s[42:43], 0, v[134:135]
	s_mov_b32 m0, s33
	ds_read_b128 v[200:203], v164 offset:16384
	ds_read_b128 v[204:207], v164 offset:17408
	ds_read_b128 v[208:211], v164 offset:18432
	ds_read_b128 v[212:215], v164 offset:19456
	ds_read_b128 v[216:219], v164 offset:20480
	ds_read_b128 v[220:223], v164 offset:21504
	ds_read_b128 v[224:227], v164 offset:22528
	ds_read_b128 v[228:231], v164 offset:23552
	global_load_lds_dwordx4 v[232:233], off
	s_add_i32 m0, s33, 0x2000
	s_add_u32 s80, s42, 0x80000
	v_lshl_add_u64 v[234:235], s[42:43], 0, v[138:139]
	s_addc_u32 s81, s43, 0
	s_add_i32 s33, s63, s53
	global_load_lds_dwordx4 v[234:235], off
	s_mov_b32 m0, s33
	v_lshl_add_u64 v[236:237], s[80:81], 0, v[134:135]
	global_load_lds_dwordx4 v[236:237], off
	s_add_i32 m0, s33, 0x2000
	v_lshl_add_u64 v[236:237], s[80:81], 0, v[138:139]
	global_load_lds_dwordx4 v[236:237], off
	s_waitcnt vmcnt(6) lgkmcnt(0)
	s_barrier
	s_setprio 1
	v_mfma_f32_16x16x32_bf16 v[62:65], v[154:157], v[200:203], v[62:65]
	v_mfma_f32_16x16x32_bf16 v[58:61], v[176:179], v[200:203], v[58:61]
	v_mfma_f32_16x16x32_bf16 v[46:49], v[154:157], v[208:211], v[46:49]
	v_mfma_f32_16x16x32_bf16 v[42:45], v[176:179], v[208:211], v[42:45]
	v_mfma_f32_16x16x32_bf16 v[30:33], v[154:157], v[216:219], v[30:33]
	v_mfma_f32_16x16x32_bf16 v[26:29], v[176:179], v[216:219], v[26:29]
	v_mfma_f32_16x16x32_bf16 v[14:17], v[154:157], v[224:227], v[14:17]
	v_mfma_f32_16x16x32_bf16 v[10:13], v[176:179], v[224:227], v[10:13]
	v_mfma_f32_16x16x32_bf16 v[62:65], v[172:175], v[204:207], v[62:65]
	v_mfma_f32_16x16x32_bf16 v[58:61], v[180:183], v[204:207], v[58:61]
	v_mfma_f32_16x16x32_bf16 v[46:49], v[172:175], v[212:215], v[46:49]
	v_mfma_f32_16x16x32_bf16 v[42:45], v[180:183], v[212:215], v[42:45]
	v_mfma_f32_16x16x32_bf16 v[30:33], v[172:175], v[220:223], v[30:33]
	v_mfma_f32_16x16x32_bf16 v[26:29], v[180:183], v[220:223], v[26:29]
	v_mfma_f32_16x16x32_bf16 v[14:17], v[172:175], v[228:231], v[14:17]
	v_mfma_f32_16x16x32_bf16 v[10:13], v[180:183], v[228:231], v[10:13]
	s_setprio 0
	s_setprio 1
	v_mfma_f32_16x16x32_bf16 v[54:57], v[184:187], v[200:203], v[54:57]
	v_mfma_f32_16x16x32_bf16 v[50:53], v[192:195], v[200:203], v[50:53]
	v_mfma_f32_16x16x32_bf16 v[38:41], v[184:187], v[208:211], v[38:41]
	v_mfma_f32_16x16x32_bf16 v[34:37], v[192:195], v[208:211], v[34:37]
	v_mfma_f32_16x16x32_bf16 v[22:25], v[184:187], v[216:219], v[22:25]
	v_mfma_f32_16x16x32_bf16 v[18:21], v[192:195], v[216:219], v[18:21]
	v_mfma_f32_16x16x32_bf16 v[6:9], v[184:187], v[224:227], v[6:9]
	v_mfma_f32_16x16x32_bf16 v[2:5], v[192:195], v[224:227], v[2:5]
	v_mfma_f32_16x16x32_bf16 v[54:57], v[188:191], v[204:207], v[54:57]
	v_mfma_f32_16x16x32_bf16 v[50:53], v[196:199], v[204:207], v[50:53]
	v_mfma_f32_16x16x32_bf16 v[38:41], v[188:191], v[212:215], v[38:41]
	v_mfma_f32_16x16x32_bf16 v[34:37], v[196:199], v[212:215], v[34:37]
	v_mfma_f32_16x16x32_bf16 v[22:25], v[188:191], v[220:223], v[22:25]
	v_mfma_f32_16x16x32_bf16 v[18:21], v[196:199], v[220:223], v[18:21]
	v_mfma_f32_16x16x32_bf16 v[6:9], v[188:191], v[228:231], v[6:9]
	v_mfma_f32_16x16x32_bf16 v[2:5], v[196:199], v[228:231], v[2:5]
	s_setprio 0
	s_barrier
; #define PG8_STAGE(bufoff, gbase, voff) do { _Pragma("unroll") for (int _i = 0; _i < 2; ++_i) \
;         __builtin_amdgcn_global_load_lds((const unsigned*)((const char*)(gbase) + (voff)[_i]), (PG8_LAS unsigned*)(lds + (bufoff) + ldsw + _i * 8192), 16, 0, 0); } while (0)
; #define PG8_LDA(dst, b, h) do { _Pragma("unroll") for (int m = 0; m < 4; ++m) _Pragma("unroll") for (int k = 0; k < 2; ++k) dst[m][k] = *(const PG8_LAS bf16x8*)(lds + PG8_SA(b, h) + aoff + m * 2048 + k * 1024); } while (0)
; #define PG8_LDB(dst, b, h) do { _Pragma("unroll") for (int n = 0; n < 2; ++n) _Pragma("unroll") for (int k = 0; k < 2; ++k) dst[n][k] = *(const PG8_LAS bf16x8*)(lds + PG8_SB(b, h) + boff + n * 2048 + k * 1024); } while (0)
; #define PG8_MMA(ai, bj, At, Bt) do { __builtin_amdgcn_s_setprio(1); _Pragma("unroll") for (int m = 0; m < 4; ++m) _Pragma("unroll") for (int n = 0; n < 2; ++n) _Pragma("unroll") for (int k = 0; k < 2; ++k) \
;         acc[ai][bj][m][n] = __builtin_amdgcn_mfma_f32_16x16x32_bf16(Bt[n][k], At[m][k], acc[ai][bj][m][n], 0, 0, 0); __builtin_amdgcn_s_setprio(0); } while (0)
; #define PG8_WAIT_V(n) asm volatile("s_waitcnt vmcnt(" #n ")" ::: "memory")
; #define PG8_WAIT_L(n) asm volatile("s_waitcnt lgkmcnt(" #n ")" ::: "memory")
; #define PG8_BAR __builtin_amdgcn_s_barrier()
; #define PG8_SCHED __builtin_amdgcn_sched_barrier(0)
; template <class Epi, class Sched, bool ALIGN_EPI = false, bool SP2 = false, bool KSEG = false>
; __device__ __forceinline__ void gemm_phase(PG8_LAS unsigned char* lds, const Gemm g, const Sched& S, const Epi& E) {
;     ...
;             PG8_LDB(B0, 1, 0); PG8_LDB(B1, 1, 1); PG8_SCHED; PG8_LDA(At, 1, 0); PG8_STAGE(PG8_SA(0, 1), a2 + hstep, voffA);
;             PG8_WAIT_V(8); PG8_WAIT_L(0); PG8_BAR; PG8_MMA(0, 0, At, B0); PG8_MMA(0, 1, At, B1); PG8_BAR; PG8_SCHED;
	s_add_i32 s33, 0, 0x18000
	s_add_i32 s80, 0, 0x1c000
	v_add_u32_e32 v180, s33, v163
	v_add_u32_e32 v196, s80, v163
	ds_read_b128 v[154:157], v180
	ds_read_b128 v[172:175], v180 offset:1024
	ds_read_b128 v[176:179], v180 offset:2048
	ds_read_b128 v[180:183], v180 offset:3072
	ds_read_b128 v[184:187], v196
	ds_read_b128 v[188:191], v196 offset:1024
	ds_read_b128 v[192:195], v196 offset:2048
	ds_read_b128 v[196:199], v196 offset:3072
	ds_read_b128 v[200:203], v164 offset:32768
	ds_read_b128 v[204:207], v164 offset:33792
	ds_read_b128 v[208:211], v164 offset:34816
	ds_read_b128 v[212:215], v164 offset:35840
	ds_read_b128 v[216:219], v164 offset:36864
	ds_read_b128 v[220:223], v164 offset:37888
	ds_read_b128 v[224:227], v164 offset:38912
	ds_read_b128 v[228:231], v164 offset:39936
	s_mov_b32 m0, s55
	v_lshl_add_u64 v[240:241], s[44:45], 0, v[132:133]
	global_load_lds_dwordx4 v[240:241], off
	s_mov_b32 m0, s56
	v_lshl_add_u64 v[240:241], s[44:45], 0, v[136:137]
	global_load_lds_dwordx4 v[240:241], off
	s_add_u32 s44, s44, 0x80000
	s_addc_u32 s45, s45, 0
	s_mov_b32 m0, s57
	v_lshl_add_u64 v[240:241], s[44:45], 0, v[132:133]
	global_load_lds_dwordx4 v[240:241], off
	s_mov_b32 m0, s58
	v_lshl_add_u64 v[240:241], s[44:45], 0, v[136:137]
	global_load_lds_dwordx4 v[240:241], off
	s_waitcnt vmcnt(8) lgkmcnt(0)
	s_barrier
	s_setprio 1
	v_mfma_f32_16x16x32_bf16 v[126:129], v[154:157], v[200:203], v[126:129]
	v_mfma_f32_16x16x32_bf16 v[122:125], v[176:179], v[200:203], v[122:125]
	v_mfma_f32_16x16x32_bf16 v[110:113], v[154:157], v[208:211], v[110:113]
	v_mfma_f32_16x16x32_bf16 v[106:109], v[176:179], v[208:211], v[106:109]
	v_mfma_f32_16x16x32_bf16 v[94:97], v[154:157], v[216:219], v[94:97]
	v_mfma_f32_16x16x32_bf16 v[90:93], v[176:179], v[216:219], v[90:93]
	v_mfma_f32_16x16x32_bf16 v[78:81], v[154:157], v[224:227], v[78:81]
	v_mfma_f32_16x16x32_bf16 v[74:77], v[176:179], v[224:227], v[74:77]
	v_mfma_f32_16x16x32_bf16 v[126:129], v[172:175], v[204:207], v[126:129]
	v_mfma_f32_16x16x32_bf16 v[122:125], v[180:183], v[204:207], v[122:125]
	v_mfma_f32_16x16x32_bf16 v[110:113], v[172:175], v[212:215], v[110:113]
	v_mfma_f32_16x16x32_bf16 v[106:109], v[180:183], v[212:215], v[106:109]
	v_mfma_f32_16x16x32_bf16 v[94:97], v[172:175], v[220:223], v[94:97]
	v_mfma_f32_16x16x32_bf16 v[90:93], v[180:183], v[220:223], v[90:93]
	v_mfma_f32_16x16x32_bf16 v[78:81], v[172:175], v[228:231], v[78:81]
	v_mfma_f32_16x16x32_bf16 v[74:77], v[180:183], v[228:231], v[74:77]
	s_setprio 0
	s_setprio 1
	v_mfma_f32_16x16x32_bf16 v[118:121], v[184:187], v[200:203], v[118:121]
	v_mfma_f32_16x16x32_bf16 v[114:117], v[192:195], v[200:203], v[114:117]
	v_mfma_f32_16x16x32_bf16 v[102:105], v[184:187], v[208:211], v[102:105]
	v_mfma_f32_16x16x32_bf16 v[98:101], v[192:195], v[208:211], v[98:101]
	v_mfma_f32_16x16x32_bf16 v[86:89], v[184:187], v[216:219], v[86:89]
	v_mfma_f32_16x16x32_bf16 v[82:85], v[192:195], v[216:219], v[82:85]
	v_mfma_f32_16x16x32_bf16 v[70:73], v[184:187], v[224:227], v[70:73]
	v_mfma_f32_16x16x32_bf16 v[66:69], v[192:195], v[224:227], v[66:69]
	v_mfma_f32_16x16x32_bf16 v[118:121], v[188:191], v[204:207], v[118:121]
	v_mfma_f32_16x16x32_bf16 v[114:117], v[196:199], v[204:207], v[114:117]
	v_mfma_f32_16x16x32_bf16 v[102:105], v[188:191], v[212:215], v[102:105]
	v_mfma_f32_16x16x32_bf16 v[98:101], v[196:199], v[212:215], v[98:101]
	v_mfma_f32_16x16x32_bf16 v[86:89], v[188:191], v[220:223], v[86:89]
	v_mfma_f32_16x16x32_bf16 v[82:85], v[196:199], v[220:223], v[82:85]
	v_mfma_f32_16x16x32_bf16 v[70:73], v[188:191], v[228:231], v[70:73]
	v_mfma_f32_16x16x32_bf16 v[66:69], v[196:199], v[228:231], v[66:69]
	s_setprio 0
	s_barrier
; #define PG8_STAGE(bufoff, gbase, voff) do { _Pragma("unroll") for (int _i = 0; _i < 2; ++_i) \
;         __builtin_amdgcn_global_load_lds((const unsigned*)((const char*)(gbase) + (voff)[_i]), (PG8_LAS unsigned*)(lds + (bufoff) + ldsw + _i * 8192), 16, 0, 0); } while (0)
; #define PG8_LDA(dst, b, h) do { _Pragma("unroll") for (int m = 0; m < 4; ++m) _Pragma("unroll") for (int k = 0; k < 2; ++k) dst[m][k] = *(const PG8_LAS bf16x8*)(lds + PG8_SA(b, h) + aoff + m * 2048 + k * 1024); } while (0)
; #define PG8_MMA(ai, bj, At, Bt) do { __builtin_amdgcn_s_setprio(1); _Pragma("unroll") for (int m = 0; m < 4; ++m) _Pragma("unroll") for (int n = 0; n < 2; ++n) _Pragma("unroll") for (int k = 0; k < 2; ++k) \
;         acc[ai][bj][m][n] = __builtin_amdgcn_mfma_f32_16x16x32_bf16(Bt[n][k], At[m][k], acc[ai][bj][m][n], 0, 0, 0); __builtin_amdgcn_s_setprio(0); } while (0)
; #define PG8_WAIT_V(n) asm volatile("s_waitcnt vmcnt(" #n ")" ::: "memory")
; #define PG8_WAIT_L(n) asm volatile("s_waitcnt lgkmcnt(" #n ")" ::: "memory")
; #define PG8_BAR __builtin_amdgcn_s_barrier()
; #define PG8_SCHED __builtin_amdgcn_sched_barrier(0)
; template <class Epi, class Sched, bool ALIGN_EPI = false, bool SP2 = false, bool KSEG = false>
; __device__ __forceinline__ void gemm_phase(PG8_LAS unsigned char* lds, const Gemm g, const Sched& S, const Epi& E) {
;     ...
;         for (int t = 0; t < nt; t += 2) {
;             const bool last = (t == nt - 2);
;             const char* a1 = cA + (size_t)(t + 1) * kstep;
;             const char* a2 = last ? nA : cA + (size_t)(t + 2) * kstep; const char* b2 = last ? nB : cB + (size_t)(t + 2) * kstep;
;             const char* a3 = a2 + kstep; const char* b3 = b2 + kstep;
;     ...
;             PG8_LDA(At, 1, 1); PG8_STAGE(PG8_SB(1, 0), b3, voffB); PG8_STAGE(PG8_SB(1, 1), b3 + hstep, voffB); PG8_STAGE(PG8_SA(1, 0), a3, voffA);
;             PG8_WAIT_V(8); PG8_WAIT_L(0); PG8_BAR; PG8_MMA(1, 0, At, B0); PG8_MMA(1, 1, At, B1); PG8_BAR; PG8_SCHED;
	s_add_i32 s33, s33, s53
	v_lshl_add_u64 v[232:233], v[232:233], 0, s[12:13]
	s_mov_b32 m0, s33
	ds_read_b128 v[200:203], v164 offset:49152
	ds_read_b128 v[204:207], v164 offset:50176
	ds_read_b128 v[208:211], v164 offset:51200
	ds_read_b128 v[212:215], v164 offset:52224
	ds_read_b128 v[216:219], v164 offset:53248
	ds_read_b128 v[220:223], v164 offset:54272
	ds_read_b128 v[224:227], v164 offset:55296
	ds_read_b128 v[228:231], v164 offset:56320
	global_load_lds_dwordx4 v[232:233], off
	s_add_i32 m0, s33, 0x2000
	s_add_u32 s42, s42, 0x80080
	v_lshl_add_u64 v[232:233], v[234:235], 0, s[12:13]
	s_addc_u32 s43, s43, 0
	s_add_i32 s33, s80, s53
	global_load_lds_dwordx4 v[232:233], off
	s_mov_b32 m0, s33
	v_lshl_add_u64 v[232:233], s[42:43], 0, v[134:135]
	global_load_lds_dwordx4 v[232:233], off
	s_add_i32 m0, s33, 0x2000
	v_lshl_add_u64 v[232:233], s[42:43], 0, v[138:139]
	global_load_lds_dwordx4 v[232:233], off
	s_waitcnt vmcnt(6) lgkmcnt(0)
	s_barrier
	s_setprio 1
	v_mfma_f32_16x16x32_bf16 v[62:65], v[154:157], v[200:203], v[62:65]
	v_mfma_f32_16x16x32_bf16 v[58:61], v[176:179], v[200:203], v[58:61]
	v_mfma_f32_16x16x32_bf16 v[46:49], v[154:157], v[208:211], v[46:49]
	v_mfma_f32_16x16x32_bf16 v[42:45], v[176:179], v[208:211], v[42:45]
	v_mfma_f32_16x16x32_bf16 v[30:33], v[154:157], v[216:219], v[30:33]
	v_mfma_f32_16x16x32_bf16 v[26:29], v[176:179], v[216:219], v[26:29]
	v_mfma_f32_16x16x32_bf16 v[14:17], v[154:157], v[224:227], v[14:17]
	v_mfma_f32_16x16x32_bf16 v[10:13], v[176:179], v[224:227], v[10:13]
	v_mfma_f32_16x16x32_bf16 v[62:65], v[172:175], v[204:207], v[62:65]
	v_mfma_f32_16x16x32_bf16 v[58:61], v[180:183], v[204:207], v[58:61]
	v_mfma_f32_16x16x32_bf16 v[46:49], v[172:175], v[212:215], v[46:49]
	v_mfma_f32_16x16x32_bf16 v[42:45], v[180:183], v[212:215], v[42:45]
	v_mfma_f32_16x16x32_bf16 v[30:33], v[172:175], v[220:223], v[30:33]
	v_mfma_f32_16x16x32_bf16 v[26:29], v[180:183], v[220:223], v[26:29]
	v_mfma_f32_16x16x32_bf16 v[14:17], v[172:175], v[228:231], v[14:17]
	v_mfma_f32_16x16x32_bf16 v[10:13], v[180:183], v[228:231], v[10:13]
	s_setprio 0
	s_setprio 1
	v_mfma_f32_16x16x32_bf16 v[54:57], v[184:187], v[200:203], v[54:57]
	s_add_i32 s79, s79, 2
	v_mfma_f32_16x16x32_bf16 v[50:53], v[192:195], v[200:203], v[50:53]
	s_add_u32 s40, s40, 0x100
	v_mfma_f32_16x16x32_bf16 v[38:41], v[184:187], v[208:211], v[38:41]
	s_addc_u32 s41, s41, 0
	v_mfma_f32_16x16x32_bf16 v[34:37], v[192:195], v[208:211], v[34:37]
	s_add_u32 s67, s67, 0x100
	v_mfma_f32_16x16x32_bf16 v[22:25], v[184:187], v[216:219], v[22:25]
	s_addc_u32 s78, s78, 0
	v_mfma_f32_16x16x32_bf16 v[18:21], v[192:195], v[216:219], v[18:21]
	s_add_u32 s33, s40, 0xfff80080
	v_mfma_f32_16x16x32_bf16 v[6:9], v[184:187], v[224:227], v[6:9]
	s_addc_u32 s42, s41, -1
	v_mfma_f32_16x16x32_bf16 v[2:5], v[192:195], v[224:227], v[2:5]
	s_cmp_eq_u32 s79, 28
	v_mfma_f32_16x16x32_bf16 v[54:57], v[188:191], v[204:207], v[54:57]
	s_cselect_b32 s45, s29, s42
	v_mfma_f32_16x16x32_bf16 v[50:53], v[196:199], v[204:207], v[50:53]
	s_cselect_b32 s44, s65, s33
	v_mfma_f32_16x16x32_bf16 v[38:41], v[188:191], v[212:215], v[38:41]
	s_cselect_b32 s43, s27, s78
	v_mfma_f32_16x16x32_bf16 v[34:37], v[196:199], v[212:215], v[34:37]
	s_cselect_b32 s42, s66, s67
	v_mfma_f32_16x16x32_bf16 v[22:25], v[188:191], v[220:223], v[22:25]
	s_add_u32 s98, s40, 0xfff80000
	v_mfma_f32_16x16x32_bf16 v[18:21], v[196:199], v[220:223], v[18:21]
	s_addc_u32 s99, s41, -1
	v_mfma_f32_16x16x32_bf16 v[6:9], v[188:191], v[228:231], v[6:9]
	s_cmp_lt_u32 s79, 30
	v_mfma_f32_16x16x32_bf16 v[2:5], v[196:199], v[228:231], v[2:5]
	s_setprio 0
	s_barrier
	s_cbranch_scc1 .LBB0_581
	s_andn2_b64 vcc, exec, s[24:25]
	s_cbranch_vccnz .LBB0_584
	s_barrier

; #define PG8_STAGE(bufoff, gbase, voff) do { _Pragma("unroll") for (int _i = 0; _i < 2; ++_i) \
;         __builtin_amdgcn_global_load_lds((const unsigned*)((const char*)(gbase) + (voff)[_i]), (PG8_LAS unsigned*)(lds + (bufoff) + ldsw + _i * 8192), 16, 0, 0); } while (0)
; #define PG8_LDA(dst, b, h) do { _Pragma("unroll") for (int m = 0; m < 4; ++m) _Pragma("unroll") for (int k = 0; k < 2; ++k) dst[m][k] = *(const PG8_LAS bf16x8*)(lds + PG8_SA(b, h) + aoff + m * 2048 + k * 1024); } while (0)
; #define PG8_LDB(dst, b, h) do { _Pragma("unroll") for (int n = 0; n < 2; ++n) _Pragma("unroll") for (int k = 0; k < 2; ++k) dst[n][k] = *(const PG8_LAS bf16x8*)(lds + PG8_SB(b, h) + boff + n * 2048 + k * 1024); } while (0)
; #define PG8_MMA(ai, bj, At, Bt) do { __builtin_amdgcn_s_setprio(1); _Pragma("unroll") for (int m = 0; m < 4; ++m) _Pragma("unroll") for (int n = 0; n < 2; ++n) _Pragma("unroll") for (int k = 0; k < 2; ++k) \
;         acc[ai][bj][m][n] = __builtin_amdgcn_mfma_f32_16x16x32_bf16(Bt[n][k], At[m][k], acc[ai][bj][m][n], 0, 0, 0); __builtin_amdgcn_s_setprio(0); } while (0)
; #define PG8_WAIT_V(n) asm volatile("s_waitcnt vmcnt(" #n ")" ::: "memory")
; #define PG8_WAIT_L(n) asm volatile("s_waitcnt lgkmcnt(" #n ")" ::: "memory")
; #define PG8_BAR __builtin_amdgcn_s_barrier()
; #define PG8_SCHED __builtin_amdgcn_sched_barrier(0)
; template <class Epi, class Sched, bool ALIGN_EPI = false, bool SP2 = false, bool KSEG = false>
; __device__ __forceinline__ void gemm_phase(PG8_LAS unsigned char* lds, const Gemm g, const Sched& S, const Epi& E) {
;     ...
;             PG8_LDB(B0, 0, 0); PG8_LDB(B1, 0, 1); PG8_SCHED; PG8_LDA(At, 0, 0); PG8_STAGE(PG8_SA(1, 1), a1 + hstep, voffA);
;             PG8_WAIT_V(8); PG8_WAIT_L(0); PG8_BAR; PG8_MMA(0, 0, At, B0); PG8_MMA(0, 1, At, B1); PG8_BAR; PG8_SCHED;
;             PG8_LDA(At, 0, 1); PG8_STAGE(PG8_SB(0, 0), b2, voffB); PG8_STAGE(PG8_SB(0, 1), b2 + hstep, voffB); PG8_STAGE(PG8_SA(0, 0), a2, voffA);
;             PG8_WAIT_V(8); PG8_WAIT_L(0); PG8_BAR; PG8_MMA(1, 0, At, B0); PG8_MMA(1, 1, At, B1); PG8_BAR; PG8_SCHED;
.LBB0_621:
	ds_read_b128 v[146:149], v1
	ds_read_b128 v[156:159], v1 offset:1024
	ds_read_b128 v[160:163], v1 offset:2048
	ds_read_b128 v[164:167], v1 offset:3072
	ds_read_b128 v[168:171], v153
	ds_read_b128 v[172:175], v153 offset:1024
	ds_read_b128 v[176:179], v153 offset:2048
	ds_read_b128 v[180:183], v153 offset:3072
	ds_read_b128 v[184:187], v154
	ds_read_b128 v[188:191], v154 offset:1024
	ds_read_b128 v[192:195], v154 offset:2048
	ds_read_b128 v[196:199], v154 offset:3072
	ds_read_b128 v[200:203], v154 offset:4096
	ds_read_b128 v[204:207], v154 offset:5120
	ds_read_b128 v[208:211], v154 offset:6144
	ds_read_b128 v[212:215], v154 offset:7168
	s_mov_b32 m0, s40
	v_lshl_add_u64 v[216:217], s[98:99], 0, v[140:141]
	global_load_lds_dwordx4 v[216:217], off
	s_mov_b32 m0, s41
	v_lshl_add_u64 v[216:217], s[98:99], 0, v[142:143]
	global_load_lds_dwordx4 v[216:217], off
	v_lshl_add_u64 v[216:217], s[24:25], 0, v[132:133]
	s_add_i32 m0, s31, 0xc000
	s_nop 0
	global_load_lds_dwordx4 v[216:217], off
	s_add_i32 m0, s31, 0xe000
	v_lshl_add_u64 v[216:217], s[24:25], 0, v[134:135]
	global_load_lds_dwordx4 v[216:217], off
	s_waitcnt vmcnt(8) lgkmcnt(0)
	s_barrier
	s_setprio 1
	v_mfma_f32_16x16x32_bf16 v[126:129], v[146:149], v[184:187], v[126:129]
	v_mfma_f32_16x16x32_bf16 v[122:125], v[160:163], v[184:187], v[122:125]
	v_mfma_f32_16x16x32_bf16 v[110:113], v[146:149], v[192:195], v[110:113]
	v_mfma_f32_16x16x32_bf16 v[106:109], v[160:163], v[192:195], v[106:109]
	v_mfma_f32_16x16x32_bf16 v[94:97], v[146:149], v[200:203], v[94:97]
	v_mfma_f32_16x16x32_bf16 v[90:93], v[160:163], v[200:203], v[90:93]
	v_mfma_f32_16x16x32_bf16 v[78:81], v[146:149], v[208:211], v[78:81]
	v_mfma_f32_16x16x32_bf16 v[74:77], v[160:163], v[208:211], v[74:77]
	v_mfma_f32_16x16x32_bf16 v[126:129], v[156:159], v[188:191], v[126:129]
	v_mfma_f32_16x16x32_bf16 v[122:125], v[164:167], v[188:191], v[122:125]
	v_mfma_f32_16x16x32_bf16 v[110:113], v[156:159], v[196:199], v[110:113]
	v_mfma_f32_16x16x32_bf16 v[106:109], v[164:167], v[196:199], v[106:109]
	v_mfma_f32_16x16x32_bf16 v[94:97], v[156:159], v[204:207], v[94:97]
	v_mfma_f32_16x16x32_bf16 v[90:93], v[164:167], v[204:207], v[90:93]
	v_mfma_f32_16x16x32_bf16 v[78:81], v[156:159], v[212:215], v[78:81]
	v_mfma_f32_16x16x32_bf16 v[74:77], v[164:167], v[212:215], v[74:77]
	s_setprio 0
	s_setprio 1
	v_mfma_f32_16x16x32_bf16 v[118:121], v[168:171], v[184:187], v[118:121]
	v_mfma_f32_16x16x32_bf16 v[114:117], v[176:179], v[184:187], v[114:117]
	v_mfma_f32_16x16x32_bf16 v[102:105], v[168:171], v[192:195], v[102:105]
	v_mfma_f32_16x16x32_bf16 v[98:101], v[176:179], v[192:195], v[98:101]
	v_mfma_f32_16x16x32_bf16 v[86:89], v[168:171], v[200:203], v[86:89]
	v_mfma_f32_16x16x32_bf16 v[82:85], v[176:179], v[200:203], v[82:85]
	v_mfma_f32_16x16x32_bf16 v[70:73], v[168:171], v[208:211], v[70:73]
	v_mfma_f32_16x16x32_bf16 v[66:69], v[176:179], v[208:211], v[66:69]
	v_mfma_f32_16x16x32_bf16 v[118:121], v[172:175], v[188:191], v[118:121]
	v_mfma_f32_16x16x32_bf16 v[114:117], v[180:183], v[188:191], v[114:117]
	v_mfma_f32_16x16x32_bf16 v[102:105], v[172:175], v[196:199], v[102:105]
	v_mfma_f32_16x16x32_bf16 v[98:101], v[180:183], v[196:199], v[98:101]
	v_mfma_f32_16x16x32_bf16 v[86:89], v[172:175], v[204:207], v[86:89]
	v_mfma_f32_16x16x32_bf16 v[82:85], v[180:183], v[204:207], v[82:85]
	v_mfma_f32_16x16x32_bf16 v[70:73], v[172:175], v[212:215], v[70:73]
	v_mfma_f32_16x16x32_bf16 v[66:69], v[180:183], v[212:215], v[66:69]
	s_setprio 0
	s_barrier
	s_add_i32 s33, s42, s30
	v_lshl_add_u64 v[216:217], s[26:27], 0, v[130:131]
	s_mov_b32 m0, s33
	ds_read_b128 v[184:187], v154 offset:16384
	ds_read_b128 v[188:191], v154 offset:17408
	ds_read_b128 v[192:195], v154 offset:18432
	ds_read_b128 v[196:199], v154 offset:19456
	ds_read_b128 v[200:203], v154 offset:20480
	ds_read_b128 v[204:207], v154 offset:21504
	ds_read_b128 v[208:211], v154 offset:22528
	ds_read_b128 v[212:215], v154 offset:23552
	global_load_lds_dwordx4 v[216:217], off
	s_add_i32 m0, s33, 0x2000
	s_add_u32 s54, s26, 0x160000
	v_lshl_add_u64 v[218:219], s[26:27], 0, v[144:145]
	s_addc_u32 s55, s27, 0
	s_add_i32 s33, s43, s30
	global_load_lds_dwordx4 v[218:219], off
	s_mov_b32 m0, s33
	v_lshl_add_u64 v[220:221], s[54:55], 0, v[130:131]
	global_load_lds_dwordx4 v[220:221], off
	s_add_i32 m0, s33, 0x2000
	v_lshl_add_u64 v[220:221], s[54:55], 0, v[144:145]
	global_load_lds_dwordx4 v[220:221], off
	s_waitcnt vmcnt(6) lgkmcnt(0)
	s_barrier
	s_setprio 1
	v_mfma_f32_16x16x32_bf16 v[62:65], v[146:149], v[184:187], v[62:65]
	v_mfma_f32_16x16x32_bf16 v[58:61], v[160:163], v[184:187], v[58:61]
	v_mfma_f32_16x16x32_bf16 v[46:49], v[146:149], v[192:195], v[46:49]
	v_mfma_f32_16x16x32_bf16 v[42:45], v[160:163], v[192:195], v[42:45]
	v_mfma_f32_16x16x32_bf16 v[30:33], v[146:149], v[200:203], v[30:33]
	v_mfma_f32_16x16x32_bf16 v[26:29], v[160:163], v[200:203], v[26:29]
	v_mfma_f32_16x16x32_bf16 v[14:17], v[146:149], v[208:211], v[14:17]
	v_mfma_f32_16x16x32_bf16 v[10:13], v[160:163], v[208:211], v[10:13]
	v_mfma_f32_16x16x32_bf16 v[62:65], v[156:159], v[188:191], v[62:65]
	v_mfma_f32_16x16x32_bf16 v[58:61], v[164:167], v[188:191], v[58:61]
	v_mfma_f32_16x16x32_bf16 v[46:49], v[156:159], v[196:199], v[46:49]
	v_mfma_f32_16x16x32_bf16 v[42:45], v[164:167], v[196:199], v[42:45]
	v_mfma_f32_16x16x32_bf16 v[30:33], v[156:159], v[204:207], v[30:33]
	v_mfma_f32_16x16x32_bf16 v[26:29], v[164:167], v[204:207], v[26:29]
	v_mfma_f32_16x16x32_bf16 v[14:17], v[156:159], v[212:215], v[14:17]
	v_mfma_f32_16x16x32_bf16 v[10:13], v[164:167], v[212:215], v[10:13]
	s_setprio 0
	s_setprio 1
	v_mfma_f32_16x16x32_bf16 v[54:57], v[168:171], v[184:187], v[54:57]
	v_mfma_f32_16x16x32_bf16 v[50:53], v[176:179], v[184:187], v[50:53]
	v_mfma_f32_16x16x32_bf16 v[38:41], v[168:171], v[192:195], v[38:41]
	v_mfma_f32_16x16x32_bf16 v[34:37], v[176:179], v[192:195], v[34:37]
	v_mfma_f32_16x16x32_bf16 v[22:25], v[168:171], v[200:203], v[22:25]
	v_mfma_f32_16x16x32_bf16 v[18:21], v[176:179], v[200:203], v[18:21]
	v_mfma_f32_16x16x32_bf16 v[6:9], v[168:171], v[208:211], v[6:9]
	v_mfma_f32_16x16x32_bf16 v[2:5], v[176:179], v[208:211], v[2:5]
	v_mfma_f32_16x16x32_bf16 v[54:57], v[172:175], v[188:191], v[54:57]
	v_mfma_f32_16x16x32_bf16 v[50:53], v[180:183], v[188:191], v[50:53]
	v_mfma_f32_16x16x32_bf16 v[38:41], v[172:175], v[196:199], v[38:41]
	v_mfma_f32_16x16x32_bf16 v[34:37], v[180:183], v[196:199], v[34:37]
	v_mfma_f32_16x16x32_bf16 v[22:25], v[172:175], v[204:207], v[22:25]
	v_mfma_f32_16x16x32_bf16 v[18:21], v[180:183], v[204:207], v[18:21]
	v_mfma_f32_16x16x32_bf16 v[6:9], v[172:175], v[212:215], v[6:9]
	v_mfma_f32_16x16x32_bf16 v[2:5], v[180:183], v[212:215], v[2:5]
	s_setprio 0
	s_barrier
; #define PG8_STAGE(bufoff, gbase, voff) do { _Pragma("unroll") for (int _i = 0; _i < 2; ++_i) \
;         __builtin_amdgcn_global_load_lds((const unsigned*)((const char*)(gbase) + (voff)[_i]), (PG8_LAS unsigned*)(lds + (bufoff) + ldsw + _i * 8192), 16, 0, 0); } while (0)
; #define PG8_LDA(dst, b, h) do { _Pragma("unroll") for (int m = 0; m < 4; ++m) _Pragma("unroll") for (int k = 0; k < 2; ++k) dst[m][k] = *(const PG8_LAS bf16x8*)(lds + PG8_SA(b, h) + aoff + m * 2048 + k * 1024); } while (0)
; #define PG8_LDB(dst, b, h) do { _Pragma("unroll") for (int n = 0; n < 2; ++n) _Pragma("unroll") for (int k = 0; k < 2; ++k) dst[n][k] = *(const PG8_LAS bf16x8*)(lds + PG8_SB(b, h) + boff + n * 2048 + k * 1024); } while (0)
; #define PG8_MMA(ai, bj, At, Bt) do { __builtin_amdgcn_s_setprio(1); _Pragma("unroll") for (int m = 0; m < 4; ++m) _Pragma("unroll") for (int n = 0; n < 2; ++n) _Pragma("unroll") for (int k = 0; k < 2; ++k) \
;         acc[ai][bj][m][n] = __builtin_amdgcn_mfma_f32_16x16x32_bf16(Bt[n][k], At[m][k], acc[ai][bj][m][n], 0, 0, 0); __builtin_amdgcn_s_setprio(0); } while (0)
; #define PG8_WAIT_V(n) asm volatile("s_waitcnt vmcnt(" #n ")" ::: "memory")
; #define PG8_WAIT_L(n) asm volatile("s_waitcnt lgkmcnt(" #n ")" ::: "memory")
; #define PG8_BAR __builtin_amdgcn_s_barrier()
; #define PG8_SCHED __builtin_amdgcn_sched_barrier(0)
; template <class Epi, class Sched, bool ALIGN_EPI = false, bool SP2 = false, bool KSEG = false>
; __device__ __forceinline__ void gemm_phase(PG8_LAS unsigned char* lds, const Gemm g, const Sched& S, const Epi& E) {
;     ...
;             PG8_LDB(B0, 1, 0); PG8_LDB(B1, 1, 1); PG8_SCHED; PG8_LDA(At, 1, 0); PG8_STAGE(PG8_SA(0, 1), a2 + hstep, voffA);
;             PG8_WAIT_V(8); PG8_WAIT_L(0); PG8_BAR; PG8_MMA(0, 0, At, B0); PG8_MMA(0, 1, At, B1); PG8_BAR; PG8_SCHED;
	s_add_i32 s33, 0, 0x18000
	v_add_u32_e32 v155, s33, v150
	s_add_i32 s53, 0, 0x1c000
	ds_read_b128 v[146:149], v155
	ds_read_b128 v[156:159], v155 offset:1024
	ds_read_b128 v[160:163], v155 offset:2048
	ds_read_b128 v[164:167], v155 offset:3072
	v_add_u32_e32 v155, s53, v150
	ds_read_b128 v[168:171], v155
	ds_read_b128 v[172:175], v155 offset:1024
	ds_read_b128 v[176:179], v155 offset:2048
	ds_read_b128 v[180:183], v155 offset:3072
	ds_read_b128 v[184:187], v154 offset:32768
	ds_read_b128 v[188:191], v154 offset:33792
	ds_read_b128 v[192:195], v154 offset:34816
	ds_read_b128 v[196:199], v154 offset:35840
	ds_read_b128 v[200:203], v154 offset:36864
	ds_read_b128 v[204:207], v154 offset:37888
	ds_read_b128 v[208:211], v154 offset:38912
	ds_read_b128 v[212:215], v154 offset:39936
	s_mov_b32 m0, s31
	v_lshl_add_u64 v[224:225], s[28:29], 0, v[140:141]
	global_load_lds_dwordx4 v[224:225], off
	s_mov_b32 m0, s36
	v_lshl_add_u64 v[224:225], s[28:29], 0, v[142:143]
	global_load_lds_dwordx4 v[224:225], off
	s_add_u32 s28, s28, 0x160000
	s_addc_u32 s29, s29, 0
	s_mov_b32 m0, s37
	v_lshl_add_u64 v[224:225], s[28:29], 0, v[140:141]
	global_load_lds_dwordx4 v[224:225], off
	s_mov_b32 m0, s38
	v_lshl_add_u64 v[224:225], s[28:29], 0, v[142:143]
	global_load_lds_dwordx4 v[224:225], off
	s_waitcnt vmcnt(8) lgkmcnt(0)
	s_barrier
	s_setprio 1
	v_mfma_f32_16x16x32_bf16 v[126:129], v[146:149], v[184:187], v[126:129]
	v_mfma_f32_16x16x32_bf16 v[122:125], v[160:163], v[184:187], v[122:125]
	v_mfma_f32_16x16x32_bf16 v[110:113], v[146:149], v[192:195], v[110:113]
	v_mfma_f32_16x16x32_bf16 v[106:109], v[160:163], v[192:195], v[106:109]
	v_mfma_f32_16x16x32_bf16 v[94:97], v[146:149], v[200:203], v[94:97]
	v_mfma_f32_16x16x32_bf16 v[90:93], v[160:163], v[200:203], v[90:93]
	v_mfma_f32_16x16x32_bf16 v[78:81], v[146:149], v[208:211], v[78:81]
	v_mfma_f32_16x16x32_bf16 v[74:77], v[160:163], v[208:211], v[74:77]
	v_mfma_f32_16x16x32_bf16 v[126:129], v[156:159], v[188:191], v[126:129]
	v_mfma_f32_16x16x32_bf16 v[122:125], v[164:167], v[188:191], v[122:125]
	v_mfma_f32_16x16x32_bf16 v[110:113], v[156:159], v[196:199], v[110:113]
	v_mfma_f32_16x16x32_bf16 v[106:109], v[164:167], v[196:199], v[106:109]
	v_mfma_f32_16x16x32_bf16 v[94:97], v[156:159], v[204:207], v[94:97]
	v_mfma_f32_16x16x32_bf16 v[90:93], v[164:167], v[204:207], v[90:93]
	v_mfma_f32_16x16x32_bf16 v[78:81], v[156:159], v[212:215], v[78:81]
	v_mfma_f32_16x16x32_bf16 v[74:77], v[164:167], v[212:215], v[74:77]
	s_setprio 0
	s_setprio 1
	v_mfma_f32_16x16x32_bf16 v[118:121], v[168:171], v[184:187], v[118:121]
	v_mfma_f32_16x16x32_bf16 v[114:117], v[176:179], v[184:187], v[114:117]
	v_mfma_f32_16x16x32_bf16 v[102:105], v[168:171], v[192:195], v[102:105]
	v_mfma_f32_16x16x32_bf16 v[98:101], v[176:179], v[192:195], v[98:101]
	v_mfma_f32_16x16x32_bf16 v[86:89], v[168:171], v[200:203], v[86:89]
	v_mfma_f32_16x16x32_bf16 v[82:85], v[176:179], v[200:203], v[82:85]
	v_mfma_f32_16x16x32_bf16 v[70:73], v[168:171], v[208:211], v[70:73]
	v_mfma_f32_16x16x32_bf16 v[66:69], v[176:179], v[208:211], v[66:69]
	v_mfma_f32_16x16x32_bf16 v[118:121], v[172:175], v[188:191], v[118:121]
	v_mfma_f32_16x16x32_bf16 v[114:117], v[180:183], v[188:191], v[114:117]
	v_mfma_f32_16x16x32_bf16 v[102:105], v[172:175], v[196:199], v[102:105]
	v_mfma_f32_16x16x32_bf16 v[98:101], v[180:183], v[196:199], v[98:101]
	v_mfma_f32_16x16x32_bf16 v[86:89], v[172:175], v[204:207], v[86:89]
	v_mfma_f32_16x16x32_bf16 v[82:85], v[180:183], v[204:207], v[82:85]
	v_mfma_f32_16x16x32_bf16 v[70:73], v[172:175], v[212:215], v[70:73]
	v_mfma_f32_16x16x32_bf16 v[66:69], v[180:183], v[212:215], v[66:69]
	s_setprio 0
	s_barrier
; #define PG8_STAGE(bufoff, gbase, voff) do { _Pragma("unroll") for (int _i = 0; _i < 2; ++_i) \
;         __builtin_amdgcn_global_load_lds((const unsigned*)((const char*)(gbase) + (voff)[_i]), (PG8_LAS unsigned*)(lds + (bufoff) + ldsw + _i * 8192), 16, 0, 0); } while (0)
; #define PG8_LDA(dst, b, h) do { _Pragma("unroll") for (int m = 0; m < 4; ++m) _Pragma("unroll") for (int k = 0; k < 2; ++k) dst[m][k] = *(const PG8_LAS bf16x8*)(lds + PG8_SA(b, h) + aoff + m * 2048 + k * 1024); } while (0)
; #define PG8_MMA(ai, bj, At, Bt) do { __builtin_amdgcn_s_setprio(1); _Pragma("unroll") for (int m = 0; m < 4; ++m) _Pragma("unroll") for (int n = 0; n < 2; ++n) _Pragma("unroll") for (int k = 0; k < 2; ++k) \
;         acc[ai][bj][m][n] = __builtin_amdgcn_mfma_f32_16x16x32_bf16(Bt[n][k], At[m][k], acc[ai][bj][m][n], 0, 0, 0); __builtin_amdgcn_s_setprio(0); } while (0)
; #define PG8_WAIT_V(n) asm volatile("s_waitcnt vmcnt(" #n ")" ::: "memory")
; #define PG8_WAIT_L(n) asm volatile("s_waitcnt lgkmcnt(" #n ")" ::: "memory")
; #define PG8_BAR __builtin_amdgcn_s_barrier()
; #define PG8_SCHED __builtin_amdgcn_sched_barrier(0)
; template <class Epi, class Sched, bool ALIGN_EPI = false, bool SP2 = false, bool KSEG = false>
; __device__ __forceinline__ void gemm_phase(PG8_LAS unsigned char* lds, const Gemm g, const Sched& S, const Epi& E) {
;     ...
;         for (int t = 0; t < nt; t += 2) {
;             const bool last = (t == nt - 2);
;             const char* a1 = cA + (size_t)(t + 1) * kstep;
;             const char* a2 = last ? nA : cA + (size_t)(t + 2) * kstep; const char* b2 = last ? nB : cB + (size_t)(t + 2) * kstep;
;             const char* a3 = a2 + kstep; const char* b3 = b2 + kstep;
;     ...
;             PG8_LDA(At, 1, 1); PG8_STAGE(PG8_SB(1, 0), b3, voffB); PG8_STAGE(PG8_SB(1, 1), b3 + hstep, voffB); PG8_STAGE(PG8_SA(1, 0), a3, voffA);
;             PG8_WAIT_V(8); PG8_WAIT_L(0); PG8_BAR; PG8_MMA(1, 0, At, B0); PG8_MMA(1, 1, At, B1); PG8_BAR; PG8_SCHED;
	s_add_i32 s28, s33, s30
	v_lshl_add_u64 v[216:217], v[216:217], 0, s[12:13]
	s_mov_b32 m0, s28
	ds_read_b128 v[184:187], v154 offset:49152
	ds_read_b128 v[188:191], v154 offset:50176
	ds_read_b128 v[192:195], v154 offset:51200
	ds_read_b128 v[196:199], v154 offset:52224
	ds_read_b128 v[200:203], v154 offset:53248
	ds_read_b128 v[204:207], v154 offset:54272
	ds_read_b128 v[208:211], v154 offset:55296
	ds_read_b128 v[212:215], v154 offset:56320
	global_load_lds_dwordx4 v[216:217], off
	s_add_i32 m0, s28, 0x2000
	s_add_u32 s26, s26, 0x160080
	v_lshl_add_u64 v[216:217], v[218:219], 0, s[12:13]
	s_addc_u32 s27, s27, 0
	s_add_i32 s28, s53, s30
	global_load_lds_dwordx4 v[216:217], off
	s_mov_b32 m0, s28
	v_lshl_add_u64 v[216:217], s[26:27], 0, v[130:131]
	global_load_lds_dwordx4 v[216:217], off
	s_add_i32 m0, s28, 0x2000
	v_lshl_add_u64 v[216:217], s[26:27], 0, v[144:145]
	global_load_lds_dwordx4 v[216:217], off
	s_waitcnt vmcnt(6) lgkmcnt(0)
	s_barrier
	s_setprio 1
	v_mfma_f32_16x16x32_bf16 v[62:65], v[146:149], v[184:187], v[62:65]
	v_mfma_f32_16x16x32_bf16 v[58:61], v[160:163], v[184:187], v[58:61]
	v_mfma_f32_16x16x32_bf16 v[46:49], v[146:149], v[192:195], v[46:49]
	v_mfma_f32_16x16x32_bf16 v[42:45], v[160:163], v[192:195], v[42:45]
	v_mfma_f32_16x16x32_bf16 v[30:33], v[146:149], v[200:203], v[30:33]
	v_mfma_f32_16x16x32_bf16 v[26:29], v[160:163], v[200:203], v[26:29]
	v_mfma_f32_16x16x32_bf16 v[14:17], v[146:149], v[208:211], v[14:17]
	v_mfma_f32_16x16x32_bf16 v[10:13], v[160:163], v[208:211], v[10:13]
	v_mfma_f32_16x16x32_bf16 v[62:65], v[156:159], v[188:191], v[62:65]
	v_mfma_f32_16x16x32_bf16 v[58:61], v[164:167], v[188:191], v[58:61]
	v_mfma_f32_16x16x32_bf16 v[46:49], v[156:159], v[196:199], v[46:49]
	v_mfma_f32_16x16x32_bf16 v[42:45], v[164:167], v[196:199], v[42:45]
	v_mfma_f32_16x16x32_bf16 v[30:33], v[156:159], v[204:207], v[30:33]
	v_mfma_f32_16x16x32_bf16 v[26:29], v[164:167], v[204:207], v[26:29]
	v_mfma_f32_16x16x32_bf16 v[14:17], v[156:159], v[212:215], v[14:17]
	v_mfma_f32_16x16x32_bf16 v[10:13], v[164:167], v[212:215], v[10:13]
	s_setprio 0
	s_setprio 1
	v_mfma_f32_16x16x32_bf16 v[54:57], v[168:171], v[184:187], v[54:57]
	s_add_i32 s50, s50, 2
	v_mfma_f32_16x16x32_bf16 v[50:53], v[176:179], v[184:187], v[50:53]
	s_add_u32 s24, s24, 0x100
	v_mfma_f32_16x16x32_bf16 v[38:41], v[168:171], v[192:195], v[38:41]
	s_addc_u32 s25, s25, 0
	v_mfma_f32_16x16x32_bf16 v[34:37], v[176:179], v[192:195], v[34:37]
	s_add_u32 s48, s48, 0x100
	v_mfma_f32_16x16x32_bf16 v[22:25], v[168:171], v[200:203], v[22:25]
	s_addc_u32 s49, s49, 0
	v_mfma_f32_16x16x32_bf16 v[18:21], v[176:179], v[200:203], v[18:21]
	s_add_u32 s26, s24, 0xffea0080
	v_mfma_f32_16x16x32_bf16 v[6:9], v[168:171], v[208:211], v[6:9]
	s_addc_u32 s27, s25, -1
	v_mfma_f32_16x16x32_bf16 v[2:5], v[176:179], v[208:211], v[2:5]
	s_cmpk_eq_i32 s50, 0x54
	v_mfma_f32_16x16x32_bf16 v[54:57], v[172:175], v[188:191], v[54:57]
	s_cselect_b32 s29, s21, s27
	v_mfma_f32_16x16x32_bf16 v[50:53], v[180:183], v[188:191], v[50:53]
	s_cselect_b32 s28, s20, s26
	v_mfma_f32_16x16x32_bf16 v[38:41], v[172:175], v[196:199], v[38:41]
	s_cselect_b32 s27, s9, s49
	v_mfma_f32_16x16x32_bf16 v[34:37], v[180:183], v[196:199], v[34:37]
	s_cselect_b32 s26, s8, s48
	v_mfma_f32_16x16x32_bf16 v[22:25], v[172:175], v[204:207], v[22:25]
	s_add_u32 s98, s24, 0xffea0000
	v_mfma_f32_16x16x32_bf16 v[18:21], v[180:183], v[204:207], v[18:21]
	s_addc_u32 s99, s25, -1
	v_mfma_f32_16x16x32_bf16 v[6:9], v[172:175], v[212:215], v[6:9]
	s_cmpk_lt_u32 s50, 0x56
	v_mfma_f32_16x16x32_bf16 v[2:5], v[180:183], v[212:215], v[2:5]
	s_setprio 0
	s_barrier
	s_cbranch_scc1 .LBB0_621
	s_andn2_b64 vcc, exec, s[18:19]
	s_cbranch_vccnz .LBB0_624
	s_barrier
